# LRU scan: batched LDS reads, pass-2 reuses registers; loop-top vmcnt counted past the 16 stores
# speedup vs baseline: 1.0089x; 1.0089x over previous
; __device__ __forceinline__ float softplusf_(float x) { return fmaxf(x, 0.f) + log1pf(expf(-fabsf(x))); }
; __device__ __forceinline__ void lru_item(const Args& A, Frame& F, int l, int it) {
;     ...
;         if (tid < 128) hcar[tid] = 0.f;
;     }
;     float bgr[4], bgi[4], spl[4];
; #pragma unroll
;     for (int nt = 0; nt < 4; ++nt) {
;         const int ch = blk * 64 + 16 * nt + fr;
;         bgr[nt] = GIN(17)[((size_t)(l * 2 + dir) * 2 + 0) * D + ch];
;         bgi[nt] = GIN(17)[((size_t)(l * 2 + dir) * 2 + 1) * D + ch];
;         spl[nt] = -8.f * 1.4426950408889634f * softplusf_(-GIN(18)[(size_t)(l * 2 + dir) * D + ch]);
;     }
.LBB0_59:
	s_or_b64 exec, exec, s[8:9]
	s_movk_i32 s8, 0x80
	v_cmp_gt_i32_e32 vcc, s8, v54
	s_and_saveexec_b64 s[8:9], vcc
	v_lshl_add_u32 v0, v54, 2, 0
	v_add_u32_e32 v0, 0x1b000, v0
	ds_write_b32 v0, v1
	s_or_b64 exec, exec, s[8:9]
	s_load_dwordx4 s[8:11], s[46:47], 0x88
	s_ashr_i32 s26, s2, 6
	s_ashr_i32 s14, s37, 5
	s_lshl_b32 s15, s39, 6
	s_lshl_b64 s[12:13], s[4:5], 13
	s_waitcnt lgkmcnt(0)
	s_add_u32 s12, s8, s12
	s_waitcnt vmcnt(0)
	v_and_b32_e32 v22, 15, v54
	s_addc_u32 s13, s9, s13
	s_lshl_b64 s[4:5], s[4:5], 12
	v_or_b32_e32 v0, s15, v22
	s_add_u32 s4, s10, s4
	s_addc_u32 s5, s11, s5
	v_lshlrev_b32_e32 v0, 2, v0
	global_load_dword v7, v0, s[4:5]
	global_load_dword v4, v0, s[4:5] offset:64
	v_lshl_add_u64 v[2:3], s[12:13], 0, v[0:1]
	s_movk_i32 s20, 0x1000
	v_add_co_u32_e32 v2, vcc, s20, v2
	s_load_dwordx4 s[8:11], s[46:47], 0x70
	s_nop 0
	v_addc_co_u32_e32 v3, vcc, 0, v3, vcc
	global_load_dword v55, v0, s[12:13]
	global_load_dword v59, v0, s[12:13] offset:64
	global_load_dword v78, v0, s[12:13] offset:128
	global_load_dword v6, v0, s[4:5] offset:128
	global_load_dword v5, v0, s[4:5] offset:192
	global_load_dword v79, v0, s[12:13] offset:192
	s_mov_b32 s5, 0x3f2aaaab
	s_mov_b32 s4, 0x7f800000
	global_load_dword v83, v[2:3], off
	global_load_dword v84, v[2:3], off offset:64
	global_load_dword v85, v[2:3], off offset:128
	global_load_dword v86, v[2:3], off offset:192
	s_mov_b32 s12, 0x33800000
	v_ashrrev_i32_e32 v32, 2, v54
	v_and_b32_e32 v88, -4, v32
	v_or_b32_e32 v90, 3, v32
	v_ashrrev_i32_e32 v91, 6, v54
	s_mov_b32 s2, 0
	s_mov_b32 s20, 0x3f317218
	s_mov_b32 s29, 0x7f800000
	s_mov_b64 s[78:79], 0
	s_waitcnt vmcnt(11)
	v_mul_f32_e64 v8, |v7|, s59
	v_fma_f32 v11, |v7|, s59, -v8
	v_rndne_f32_e32 v12, v8
	v_fma_f32 v11, |v7|, s76, v11
	v_sub_f32_e32 v8, v8, v12
	v_add_f32_e32 v8, v8, v11
	v_cvt_i32_f32_e32 v12, v12
	v_exp_f32_e32 v8, v8
	s_waitcnt vmcnt(10)
	v_max_f32_e64 v9, -v4, -v4
	v_mul_f32_e64 v10, |v4|, s59
	v_cmp_ngt_f32_e64 vcc, |v7|, s77
	v_ldexp_f32 v8, v8, v12
	v_max_f32_e32 v13, 0, v9
	v_fma_f32 v9, |v4|, s59, -v10
	v_rndne_f32_e32 v14, v10
	v_cndmask_b32_e32 v8, 0, v8, vcc
	v_cmp_nlt_f32_e64 vcc, |v7|, s58
	v_max_f32_e64 v0, -v7, -v7
	v_fma_f32 v9, |v4|, s76, v9
	v_sub_f32_e32 v10, v10, v14
	v_cndmask_b32_e32 v7, v182, v8, vcc
	v_add_f32_e32 v9, v10, v9
	v_add_f32_e32 v12, 1.0, v7
	v_cvt_i32_f32_e32 v11, v14
	v_exp_f32_e32 v10, v9
	v_add_f32_e32 v14, -1.0, v12
	v_frexp_mant_f32_e32 v15, v12
	v_cvt_f64_f32_e32 v[8:9], v12
	v_sub_f32_e32 v16, v14, v12
	v_frexp_exp_i32_f64_e32 v8, v[8:9]
	v_cmp_gt_f32_e32 vcc, s5, v15
	v_sub_f32_e32 v14, v7, v14
	v_add_f32_e32 v9, 1.0, v16
	v_subbrev_co_u32_e32 v8, vcc, 0, v8, vcc
	v_add_f32_e32 v9, v14, v9
	v_sub_u32_e32 v14, 0, v8
	v_cvt_f32_i32_e32 v8, v8
	v_ldexp_f32 v12, v12, v14
	v_ldexp_f32 v9, v9, v14
	v_add_f32_e32 v14, -1.0, v12
	v_add_f32_e32 v15, 1.0, v12
	v_add_f32_e32 v16, 1.0, v14
	v_add_f32_e32 v17, -1.0, v15
	v_sub_f32_e32 v16, v12, v16
	v_sub_f32_e32 v12, v12, v17
	v_mul_f32_e32 v17, 0x3f317218, v8
	v_add_f32_e32 v16, v9, v16
	v_add_f32_e32 v9, v9, v12
	v_fma_f32 v12, v8, s19, -v17
	v_add_f32_e32 v18, v14, v16
	v_add_f32_e32 v19, v15, v9
	v_fmac_f32_e32 v12, 0xb102e308, v8
	v_sub_f32_e32 v8, v14, v18
	v_sub_f32_e32 v14, v15, v19
	v_rcp_f32_e32 v15, v19
	v_add_f32_e32 v20, v17, v12
	v_add_f32_e32 v9, v9, v14
	v_sub_f32_e32 v14, v20, v17
	v_sub_f32_e32 v12, v12, v14
	v_mul_f32_e32 v14, v18, v15
	v_add_f32_e32 v8, v16, v8
	v_mul_f32_e32 v16, v19, v14
	v_fma_f32 v17, v14, v19, -v16
	v_fmac_f32_e32 v17, v14, v9
	v_add_f32_e32 v21, v16, v17
	v_sub_f32_e32 v23, v18, v21
	v_sub_f32_e32 v16, v21, v16
	v_sub_f32_e32 v18, v18, v23
	v_sub_f32_e32 v16, v16, v17
	v_sub_f32_e32 v17, v18, v21
	v_add_f32_e32 v8, v8, v17
	v_add_f32_e32 v8, v16, v8
	v_add_f32_e32 v16, v23, v8
	v_mul_f32_e32 v17, v15, v16
	v_sub_f32_e32 v18, v23, v16
	v_mul_f32_e32 v21, v19, v17
	v_add_f32_e32 v8, v8, v18
	v_add_f32_e32 v18, v14, v17
	v_fma_f32 v19, v17, v19, -v21
	v_sub_f32_e32 v14, v18, v14
	v_fmac_f32_e32 v19, v17, v9
	v_sub_f32_e32 v9, v17, v14
	v_add_f32_e32 v14, v21, v19
	v_sub_f32_e32 v17, v14, v21
	v_sub_f32_e32 v21, v16, v14
	v_sub_f32_e32 v16, v16, v21
	v_sub_f32_e32 v14, v16, v14
	v_sub_f32_e32 v17, v17, v19
	v_add_f32_e32 v8, v8, v14
	v_add_f32_e32 v8, v17, v8
	v_add_f32_e32 v8, v21, v8
	v_mul_f32_e32 v8, v15, v8
	v_add_f32_e32 v8, v9, v8
	v_add_f32_e32 v9, v18, v8
	v_mul_f32_e32 v14, v9, v9
	v_fmamk_f32 v17, v14, 0x3e9b6dac, v171
	v_sub_f32_e32 v15, v9, v18
	v_ldexp_f32 v16, v9, 1
	v_mul_f32_e32 v9, v9, v14
	v_fmaak_f32 v14, v14, v17, 0x3f2aaada
	v_mul_f32_e32 v9, v9, v14
	v_add_f32_e32 v14, v16, v9
	v_sub_f32_e32 v8, v8, v15
	v_sub_f32_e32 v15, v14, v16
	v_ldexp_f32 v8, v8, 1
	v_sub_f32_e32 v9, v9, v15
	v_add_f32_e32 v8, v8, v9
	v_add_f32_e32 v9, v14, v8
	v_sub_f32_e32 v14, v9, v14
	v_add_f32_e32 v15, v20, v9
	v_sub_f32_e32 v8, v8, v14
	v_sub_f32_e32 v14, v15, v20
	v_sub_f32_e32 v16, v15, v14
	v_sub_f32_e32 v9, v9, v14
	v_add_f32_e32 v14, v12, v8
	v_sub_f32_e32 v16, v20, v16
	v_sub_f32_e32 v17, v14, v12
	v_add_f32_e32 v9, v9, v16
	v_sub_f32_e32 v16, v14, v17
	v_sub_f32_e32 v8, v8, v17
	v_sub_f32_e32 v12, v12, v16
	v_add_f32_e32 v9, v14, v9
	v_add_f32_e32 v8, v8, v12
	v_add_f32_e32 v12, v15, v9
	v_sub_f32_e32 v14, v12, v15
	v_sub_f32_e32 v9, v9, v14
	v_add_f32_e32 v8, v8, v9
	v_add_f32_e32 v8, v12, v8
	v_cmp_neq_f32_e32 vcc, s4, v7
	v_max_f32_e32 v0, 0, v0
	s_waitcnt vmcnt(5)
; __device__ __forceinline__ float softplusf_(float x) { return fmaxf(x, 0.f) + log1pf(expf(-fabsf(x))); }
; __device__ __forceinline__ void lru_item(const Args& A, Frame& F, int l, int it) {
;     ...
;     for (int nt = 0; nt < 4; ++nt) {
;         const int ch = blk * 64 + 16 * nt + fr;
;         bgr[nt] = GIN(17)[((size_t)(l * 2 + dir) * 2 + 0) * D + ch];
;         bgi[nt] = GIN(17)[((size_t)(l * 2 + dir) * 2 + 1) * D + ch];
;         spl[nt] = -8.f * 1.4426950408889634f * softplusf_(-GIN(18)[(size_t)(l * 2 + dir) * D + ch]);
;     }
	v_max_f32_e64 v2, -v5, -v5
	v_cndmask_b32_e32 v8, v182, v8, vcc
	v_cmp_lt_f32_e64 vcc, |v7|, s18
	s_nop 1
	v_cndmask_b32_e32 v7, v8, v7, vcc
	v_add_f32_e32 v0, v0, v7
	v_mul_f32_e32 v80, 0xc138aa3b, v0
	v_ldexp_f32 v0, v10, v11
	v_cmp_ngt_f32_e64 vcc, |v4|, s77
	s_nop 1
	v_cndmask_b32_e32 v0, 0, v0, vcc
	v_cmp_nlt_f32_e64 vcc, |v4|, s58
	s_nop 1
	v_cndmask_b32_e32 v0, v182, v0, vcc
	v_add_f32_e32 v4, 1.0, v0
	v_add_f32_e32 v7, -1.0, v4
	v_sub_f32_e32 v8, v7, v4
	v_add_f32_e32 v8, 1.0, v8
	v_sub_f32_e32 v7, v0, v7
	v_add_f32_e32 v7, v7, v8
	v_frexp_mant_f32_e32 v10, v4
	v_cvt_f64_f32_e32 v[8:9], v4
	v_frexp_exp_i32_f64_e32 v8, v[8:9]
	v_cmp_gt_f32_e32 vcc, s5, v10
	s_nop 1
	v_subbrev_co_u32_e32 v8, vcc, 0, v8, vcc
	v_sub_u32_e32 v9, 0, v8
	v_ldexp_f32 v4, v4, v9
	v_ldexp_f32 v7, v7, v9
	v_add_f32_e32 v9, -1.0, v4
	v_add_f32_e32 v12, 1.0, v4
	v_add_f32_e32 v10, 1.0, v9
	v_add_f32_e32 v14, -1.0, v12
	v_sub_f32_e32 v10, v4, v10
	v_sub_f32_e32 v4, v4, v14
	v_add_f32_e32 v4, v7, v4
	v_add_f32_e32 v10, v7, v10
	v_add_f32_e32 v7, v12, v4
	v_rcp_f32_e32 v14, v7
	v_add_f32_e32 v11, v9, v10
	v_sub_f32_e32 v9, v9, v11
	v_add_f32_e32 v9, v10, v9
	v_sub_f32_e32 v10, v12, v7
	v_add_f32_e32 v4, v4, v10
	v_mul_f32_e32 v10, v11, v14
	v_mul_f32_e32 v12, v7, v10
	v_fma_f32 v15, v10, v7, -v12
	v_fmac_f32_e32 v15, v10, v4
	v_add_f32_e32 v16, v12, v15
	v_sub_f32_e32 v17, v11, v16
	v_sub_f32_e32 v11, v11, v17
	v_sub_f32_e32 v12, v16, v12
	v_sub_f32_e32 v11, v11, v16
	v_add_f32_e32 v9, v9, v11
	v_sub_f32_e32 v11, v12, v15
	v_add_f32_e32 v9, v11, v9
	v_add_f32_e32 v11, v17, v9
	v_mul_f32_e32 v12, v14, v11
	v_mul_f32_e32 v15, v7, v12
	v_fma_f32 v7, v12, v7, -v15
	v_fmac_f32_e32 v7, v12, v4
	v_sub_f32_e32 v4, v17, v11
	v_add_f32_e32 v4, v9, v4
	v_add_f32_e32 v9, v15, v7
	v_sub_f32_e32 v16, v11, v9
	v_sub_f32_e32 v11, v11, v16
	v_sub_f32_e32 v15, v9, v15
	v_sub_f32_e32 v9, v11, v9
	v_add_f32_e32 v4, v4, v9
	v_sub_f32_e32 v7, v15, v7
	v_cvt_f32_i32_e32 v8, v8
	v_add_f32_e32 v4, v7, v4
	v_add_f32_e32 v7, v10, v12
	v_add_f32_e32 v4, v16, v4
	v_sub_f32_e32 v9, v7, v10
	v_mul_f32_e32 v4, v14, v4
	v_sub_f32_e32 v9, v12, v9
	v_add_f32_e32 v4, v9, v4
	v_mul_f32_e32 v12, 0x3f317218, v8
	v_add_f32_e32 v9, v7, v4
	v_fma_f32 v14, v8, s19, -v12
	v_mul_f32_e32 v10, v9, v9
	v_fmac_f32_e32 v14, 0xb102e308, v8
	v_sub_f32_e32 v7, v9, v7
	v_fmamk_f32 v11, v10, 0x3e9b6dac, v171
	v_sub_f32_e32 v4, v4, v7
	v_add_f32_e32 v7, v12, v14
	v_fmaak_f32 v11, v10, v11, 0x3f2aaada
	v_sub_f32_e32 v8, v7, v12
	v_ldexp_f32 v12, v9, 1
	v_mul_f32_e32 v9, v9, v10
	v_mul_f32_e32 v9, v9, v11
	v_add_f32_e32 v10, v12, v9
	v_sub_f32_e32 v11, v10, v12
	v_ldexp_f32 v4, v4, 1
	v_sub_f32_e32 v9, v9, v11
	v_add_f32_e32 v4, v4, v9
	v_add_f32_e32 v9, v10, v4
	v_sub_f32_e32 v10, v9, v10
	v_sub_f32_e32 v4, v4, v10
	v_add_f32_e32 v10, v7, v9
	v_sub_f32_e32 v11, v10, v7
	v_sub_f32_e32 v12, v10, v11
	v_sub_f32_e32 v8, v14, v8
	v_sub_f32_e32 v7, v7, v12
	v_sub_f32_e32 v9, v9, v11
	v_add_f32_e32 v7, v9, v7
	v_add_f32_e32 v9, v8, v4
	v_sub_f32_e32 v11, v9, v8
	v_sub_f32_e32 v12, v9, v11
	v_sub_f32_e32 v8, v8, v12
	v_sub_f32_e32 v4, v4, v11
	v_add_f32_e32 v7, v9, v7
	v_add_f32_e32 v4, v4, v8
	v_add_f32_e32 v8, v10, v7
	v_sub_f32_e32 v9, v8, v10
	v_sub_f32_e32 v7, v7, v9
	v_add_f32_e32 v4, v4, v7
	v_add_f32_e32 v4, v8, v4
	v_cmp_neq_f32_e32 vcc, s4, v0
	s_nop 1
	v_cndmask_b32_e32 v4, v182, v4, vcc
	v_cmp_lt_f32_e64 vcc, |v0|, s18
	s_nop 1
	v_cndmask_b32_e32 v0, v4, v0, vcc
	v_mul_f32_e64 v4, |v6|, s59
	v_fma_f32 v7, |v6|, s59, -v4
	v_rndne_f32_e32 v8, v4
	v_fma_f32 v7, |v6|, s76, v7
	v_sub_f32_e32 v4, v4, v8
	v_add_f32_e32 v4, v4, v7
	v_exp_f32_e32 v4, v4
	v_cvt_i32_f32_e32 v7, v8
	v_cmp_ngt_f32_e64 vcc, |v6|, s77
	v_add_f32_e32 v0, v13, v0
	v_mul_f32_e32 v81, 0xc138aa3b, v0
	v_ldexp_f32 v4, v4, v7
	v_cndmask_b32_e32 v4, 0, v4, vcc
	v_cmp_nlt_f32_e64 vcc, |v6|, s58
	v_max_f32_e64 v0, -v6, -v6
	v_max_f32_e32 v0, 0, v0
	v_cndmask_b32_e32 v4, v182, v4, vcc
	v_add_f32_e32 v8, 1.0, v4
	v_add_f32_e32 v6, -1.0, v8
	v_sub_f32_e32 v7, v6, v8
	v_add_f32_e32 v7, 1.0, v7
	v_sub_f32_e32 v6, v4, v6
	v_add_f32_e32 v9, v6, v7
	v_frexp_mant_f32_e32 v10, v8
	v_cvt_f64_f32_e32 v[6:7], v8
	v_frexp_exp_i32_f64_e32 v6, v[6:7]
	v_cmp_gt_f32_e32 vcc, s5, v10
	s_nop 1
	v_subbrev_co_u32_e32 v6, vcc, 0, v6, vcc
	v_sub_u32_e32 v7, 0, v6
	v_ldexp_f32 v8, v8, v7
	v_ldexp_f32 v7, v9, v7
	v_add_f32_e32 v9, -1.0, v8
	v_add_f32_e32 v12, 1.0, v8
	v_add_f32_e32 v10, 1.0, v9
	v_add_f32_e32 v13, -1.0, v12
	v_sub_f32_e32 v10, v8, v10
	v_sub_f32_e32 v8, v8, v13
	v_add_f32_e32 v10, v7, v10
	v_add_f32_e32 v7, v7, v8
	v_add_f32_e32 v8, v12, v7
	v_rcp_f32_e32 v13, v8
	v_add_f32_e32 v11, v9, v10
	v_sub_f32_e32 v9, v9, v11
	v_add_f32_e32 v9, v10, v9
	v_sub_f32_e32 v10, v12, v8
	v_add_f32_e32 v7, v7, v10
	v_mul_f32_e32 v10, v11, v13
	v_mul_f32_e32 v12, v8, v10
	v_fma_f32 v14, v10, v8, -v12
	v_fmac_f32_e32 v14, v10, v7
	v_add_f32_e32 v15, v12, v14
	v_sub_f32_e32 v16, v11, v15
	v_sub_f32_e32 v11, v11, v16
	v_sub_f32_e32 v12, v15, v12
	v_sub_f32_e32 v11, v11, v15
	v_add_f32_e32 v9, v9, v11
	v_sub_f32_e32 v11, v12, v14
	v_add_f32_e32 v9, v11, v9
	v_add_f32_e32 v11, v16, v9
	v_mul_f32_e32 v12, v13, v11
	v_mul_f32_e32 v14, v8, v12
	v_fma_f32 v8, v12, v8, -v14
	v_fmac_f32_e32 v8, v12, v7
	v_sub_f32_e32 v7, v16, v11
	v_add_f32_e32 v7, v9, v7
	v_add_f32_e32 v9, v14, v8
	v_sub_f32_e32 v15, v11, v9
	v_sub_f32_e32 v11, v11, v15
	v_sub_f32_e32 v14, v9, v14
	v_sub_f32_e32 v9, v11, v9
	v_add_f32_e32 v7, v7, v9
	v_sub_f32_e32 v8, v14, v8
	v_cvt_f32_i32_e32 v6, v6
	v_add_f32_e32 v7, v8, v7
	v_add_f32_e32 v8, v10, v12
	v_add_f32_e32 v7, v15, v7
	v_sub_f32_e32 v9, v8, v10
; __device__ __forceinline__ float softplusf_(float x) { return fmaxf(x, 0.f) + log1pf(expf(-fabsf(x))); }
; __device__ __forceinline__ void lru_item(const Args& A, Frame& F, int l, int it) {
;     ...
;         spl[nt] = -8.f * 1.4426950408889634f * softplusf_(-GIN(18)[(size_t)(l * 2 + dir) * D + ch]);
;     }
;     const int c4 = (tid & 15) * 4, chg = blk * 64 + c4;
;     f32x4 cw[4];
; #pragma unroll
;     for (int j = 0; j < 4; ++j) cw[j] = *(const f32x4*)(GIN(14) + (size_t)(l * 4 + j) * D + chg);
;     const f32x4 cb = *(const f32x4*)(GIN(15) + (size_t)l * D + chg);
;     const bf16_t* lx = WSB(WS_LX) + (size_t)b * TB * D + chg;
;     bf16_t* hout = (dir ? WSB(WS_HB) : WSB(WS_HF)) + (size_t)b * TB * D + blk * 64;
;     __syncthreads();
;     const int g4 = tid >> 4;
;     u32x2 xr[7];
;     {
;         const int pb0 = dir == 0 ? 0 : 255;
;         const int pmin = dir == 0 ? pb0 + 4 * g4 : pb0 - 4 * g4 - 3;
; #pragma unroll
;         for (int e = 0; e < 7; ++e) { const int q = pmin - 2 + e; const int qc = q < 0 ? 0 : (q >= CTXL ? CTXL - 1 : q); xr[e] = *(const u32x2*)(lx + (size_t)qc * D); }
	v_mul_f32_e32 v7, v13, v7
	v_sub_f32_e32 v9, v12, v9
	v_add_f32_e32 v7, v9, v7
	v_mul_f32_e32 v12, 0x3f317218, v6
	v_add_f32_e32 v9, v8, v7
	v_fma_f32 v13, v6, s19, -v12
	v_mul_f32_e32 v10, v9, v9
	v_fmac_f32_e32 v13, 0xb102e308, v6
	v_sub_f32_e32 v6, v9, v8
	v_fmamk_f32 v11, v10, 0x3e9b6dac, v171
	v_sub_f32_e32 v6, v7, v6
	v_add_f32_e32 v7, v12, v13
	v_fmaak_f32 v11, v10, v11, 0x3f2aaada
	v_sub_f32_e32 v8, v7, v12
	v_ldexp_f32 v12, v9, 1
	v_mul_f32_e32 v9, v9, v10
	v_mul_f32_e32 v9, v9, v11
	v_add_f32_e32 v10, v12, v9
	v_sub_f32_e32 v11, v10, v12
	v_ldexp_f32 v6, v6, 1
	v_sub_f32_e32 v9, v9, v11
	v_add_f32_e32 v6, v6, v9
	v_add_f32_e32 v9, v10, v6
	v_sub_f32_e32 v10, v9, v10
	v_sub_f32_e32 v6, v6, v10
	v_add_f32_e32 v10, v7, v9
	v_sub_f32_e32 v11, v10, v7
	v_sub_f32_e32 v12, v10, v11
	v_sub_f32_e32 v8, v13, v8
	v_sub_f32_e32 v7, v7, v12
	v_sub_f32_e32 v9, v9, v11
	v_add_f32_e32 v7, v9, v7
	v_add_f32_e32 v9, v8, v6
	v_sub_f32_e32 v11, v9, v8
	v_sub_f32_e32 v12, v9, v11
	v_sub_f32_e32 v8, v8, v12
	v_sub_f32_e32 v6, v6, v11
	v_add_f32_e32 v7, v9, v7
	v_add_f32_e32 v6, v6, v8
	v_add_f32_e32 v8, v10, v7
	v_sub_f32_e32 v9, v8, v10
	v_sub_f32_e32 v7, v7, v9
	v_add_f32_e32 v6, v6, v7
	v_add_f32_e32 v6, v8, v6
	v_cmp_neq_f32_e32 vcc, s4, v4
	s_nop 1
	v_cndmask_b32_e32 v6, v182, v6, vcc
	v_cmp_lt_f32_e64 vcc, |v4|, s18
	s_mov_b32 s18, 0x3f2aaaab
	s_nop 0
	v_cndmask_b32_e32 v4, v6, v4, vcc
	v_add_f32_e32 v0, v0, v4
	v_mul_f32_e32 v82, 0xc138aa3b, v0
	v_mul_f32_e64 v0, |v5|, s59
	v_fma_f32 v4, |v5|, s59, -v0
	v_rndne_f32_e32 v6, v0
	v_fma_f32 v4, |v5|, s76, v4
	v_sub_f32_e32 v0, v0, v6
	v_add_f32_e32 v0, v0, v4
	v_exp_f32_e32 v0, v0
	v_cvt_i32_f32_e32 v4, v6
	v_cmp_ngt_f32_e64 vcc, |v5|, s77
	v_max_f32_e32 v6, 0, v2
	v_ldexp_f32 v0, v0, v4
	v_cndmask_b32_e32 v0, 0, v0, vcc
	v_cmp_nlt_f32_e64 vcc, |v5|, s58
	s_nop 1
	v_cndmask_b32_e32 v0, v182, v0, vcc
	v_add_f32_e32 v4, 1.0, v0
	v_add_f32_e32 v2, -1.0, v4
	v_sub_f32_e32 v3, v2, v4
	v_add_f32_e32 v3, 1.0, v3
	v_sub_f32_e32 v2, v0, v2
	v_add_f32_e32 v5, v2, v3
	v_frexp_mant_f32_e32 v7, v4
	v_cvt_f64_f32_e32 v[2:3], v4
	v_frexp_exp_i32_f64_e32 v2, v[2:3]
	v_cmp_gt_f32_e32 vcc, s5, v7
	s_nop 1
	v_subbrev_co_u32_e32 v2, vcc, 0, v2, vcc
	v_sub_u32_e32 v3, 0, v2
	v_ldexp_f32 v4, v4, v3
	v_ldexp_f32 v3, v5, v3
	v_add_f32_e32 v5, -1.0, v4
	v_add_f32_e32 v9, 1.0, v4
	v_add_f32_e32 v7, 1.0, v5
	v_add_f32_e32 v10, -1.0, v9
	v_sub_f32_e32 v7, v4, v7
	v_sub_f32_e32 v4, v4, v10
	v_add_f32_e32 v7, v3, v7
	v_add_f32_e32 v3, v3, v4
	v_add_f32_e32 v4, v9, v3
	v_rcp_f32_e32 v10, v4
	v_add_f32_e32 v8, v5, v7
	v_sub_f32_e32 v5, v5, v8
	v_add_f32_e32 v5, v7, v5
	v_sub_f32_e32 v7, v9, v4
	v_add_f32_e32 v3, v3, v7
	v_mul_f32_e32 v7, v8, v10
	v_mul_f32_e32 v9, v4, v7
	v_fma_f32 v11, v7, v4, -v9
	v_fmac_f32_e32 v11, v7, v3
	v_add_f32_e32 v12, v9, v11
	v_sub_f32_e32 v13, v8, v12
	v_sub_f32_e32 v8, v8, v13
	v_sub_f32_e32 v9, v12, v9
	v_sub_f32_e32 v8, v8, v12
	v_add_f32_e32 v5, v5, v8
	v_sub_f32_e32 v8, v9, v11
	v_add_f32_e32 v5, v8, v5
	v_add_f32_e32 v8, v13, v5
	v_mul_f32_e32 v9, v10, v8
	v_mul_f32_e32 v11, v4, v9
	v_fma_f32 v4, v9, v4, -v11
	v_fmac_f32_e32 v4, v9, v3
	v_sub_f32_e32 v3, v13, v8
	v_add_f32_e32 v3, v5, v3
	v_add_f32_e32 v5, v11, v4
	v_sub_f32_e32 v12, v8, v5
	v_sub_f32_e32 v8, v8, v12
	v_sub_f32_e32 v11, v5, v11
	v_sub_f32_e32 v5, v8, v5
	v_add_f32_e32 v3, v3, v5
	v_sub_f32_e32 v4, v11, v4
	v_cvt_f32_i32_e32 v2, v2
	v_add_f32_e32 v3, v4, v3
	v_add_f32_e32 v4, v7, v9
	v_add_f32_e32 v3, v12, v3
	v_sub_f32_e32 v5, v4, v7
	v_mul_f32_e32 v3, v10, v3
	v_sub_f32_e32 v5, v9, v5
	v_add_f32_e32 v3, v5, v3
	v_mul_f32_e32 v9, 0x3f317218, v2
	v_add_f32_e32 v5, v4, v3
	v_fma_f32 v10, v2, s19, -v9
	v_mul_f32_e32 v7, v5, v5
	v_fmac_f32_e32 v10, 0xb102e308, v2
	v_sub_f32_e32 v2, v5, v4
	v_fmamk_f32 v8, v7, 0x3e9b6dac, v171
	v_sub_f32_e32 v2, v3, v2
	v_add_f32_e32 v3, v9, v10
	v_fmaak_f32 v8, v7, v8, 0x3f2aaada
	v_sub_f32_e32 v4, v3, v9
	v_ldexp_f32 v9, v5, 1
	v_mul_f32_e32 v5, v5, v7
	v_mul_f32_e32 v5, v5, v8
	v_add_f32_e32 v7, v9, v5
	v_sub_f32_e32 v8, v7, v9
	v_ldexp_f32 v2, v2, 1
	v_sub_f32_e32 v5, v5, v8
	v_add_f32_e32 v2, v2, v5
	v_add_f32_e32 v5, v7, v2
	v_sub_f32_e32 v7, v5, v7
	v_sub_f32_e32 v2, v2, v7
	v_add_f32_e32 v7, v3, v5
	v_sub_f32_e32 v8, v7, v3
	v_sub_f32_e32 v9, v7, v8
	v_sub_f32_e32 v4, v10, v4
	v_sub_f32_e32 v3, v3, v9
	v_sub_f32_e32 v5, v5, v8
	v_add_f32_e32 v3, v5, v3
	v_add_f32_e32 v5, v4, v2
	v_sub_f32_e32 v8, v5, v4
	v_sub_f32_e32 v9, v5, v8
	v_sub_f32_e32 v4, v4, v9
	v_sub_f32_e32 v2, v2, v8
	v_add_f32_e32 v3, v5, v3
	v_add_f32_e32 v2, v2, v4
	v_add_f32_e32 v4, v7, v3
	v_sub_f32_e32 v5, v4, v7
	v_sub_f32_e32 v3, v3, v5
	v_add_f32_e32 v2, v2, v3
	v_add_f32_e32 v2, v4, v2
	v_cmp_neq_f32_e32 vcc, s4, v0
	v_readlane_b32 s4, v254, 38
	v_readlane_b32 s5, v254, 39
	v_cndmask_b32_e32 v2, v182, v2, vcc
	v_cmp_lt_f32_e64 vcc, |v0|, s12
	s_mov_b32 s19, 0x33800000
	v_cmp_eq_u32_e64 s[12:13], 7, v91
	v_cndmask_b32_e32 v0, v2, v0, vcc
	v_add_f32_e32 v0, v6, v0
	v_mul_f32_e32 v87, 0xc138aa3b, v0
	v_lshlrev_b32_e32 v0, 2, v54
	v_and_b32_e32 v23, 60, v0
	v_or_b32_e32 v24, s15, v23
	v_lshlrev_b32_e32 v0, 2, v24
	s_waitcnt lgkmcnt(0)
	v_lshl_add_u64 v[10:11], s[8:9], 0, v[0:1]
	v_lshl_add_u64 v[2:3], v[10:11], 0, s[4:5]
	s_add_u32 s4, s10, s74
	v_lshl_add_u64 v[6:7], v[10:11], 0, s[66:67]
	v_lshl_add_u64 v[12:13], v[10:11], 0, s[68:69]
	v_lshl_add_u64 v[14:15], v[10:11], 0, s[70:71]
	s_addc_u32 s5, s11, s75
	s_mul_hi_i32 s10, s14, 0x480000
	s_mul_i32 s14, s14, 0x480000
	global_load_dwordx4 v[2:5], v[2:3], off
	s_nop 0
	global_load_dwordx4 v[6:9], v[6:7], off
	s_nop 0
	global_load_dwordx4 v[10:13], v[12:13], off
	s_nop 0
	global_load_dwordx4 v[14:17], v[14:15], off
	v_lshl_add_u32 v89, v23, 2, 0
	global_load_dwordx4 v[18:21], v0, s[4:5]
	s_add_u32 s4, s42, s14
	s_addc_u32 s5, s43, s10
	v_lshlrev_b32_e32 v0, 1, v24
	s_cmp_eq_u32 s45, 0
	v_lshl_add_u64 v[56:57], s[4:5], 0, v[0:1]
	v_sub_u32_e32 v0, 0xfc, v88
	s_cselect_b64 s[8:9], -1, 0
	v_cndmask_b32_e64 v33, v0, v88, s[8:9]
	v_max_i32_e32 v0, 2, v33
	v_add_u32_e32 v0, -2, v0
	v_min_u32_e32 v0, 0xff, v0
	v_lshlrev_b32_e32 v0, 11, v0
	v_lshl_add_u64 v[24:25], v[56:57], 0, v[0:1]
	v_max_i32_e32 v0, 1, v33
	v_add_u32_e32 v0, -1, v0
	v_min_u32_e32 v0, 0xff, v0
	v_lshlrev_b32_e32 v0, 11, v0
	v_lshl_add_u64 v[26:27], v[56:57], 0, v[0:1]
	v_med3_i32 v0, v33, 0, v186
	v_lshlrev_b32_e32 v0, 11, v0
	v_lshl_add_u64 v[28:29], v[56:57], 0, v[0:1]
	v_or_b32_e32 v0, 1, v33
	v_med3_i32 v0, v0, 0, v186
	v_lshlrev_b32_e32 v0, 11, v0
	v_lshl_add_u64 v[30:31], v[56:57], 0, v[0:1]
	v_or_b32_e32 v0, 2, v33
	v_med3_i32 v0, v0, 0, v186
	v_lshlrev_b32_e32 v0, 11, v0
	s_barrier
; __device__ __forceinline__ bf16_t f2bf(float f) { return (bf16_t)(pk2(f, 0.f) & 0xffffu); }
; __device__ __forceinline__ void lru_item(const Args& A, Frame& F, int l, int it) {
;     ...
;         for (int e = 0; e < 7; ++e) { const int q = pmin - 2 + e; const int qc = q < 0 ? 0 : (q >= CTXL ? CTXL - 1 : q); xr[e] = *(const u32x2*)(lx + (size_t)qc * D); }
;     }
;     for (int sc = 0; sc < NCH; ++sc) {
;         const int lo = sc < 2 ? 0 : CTXL, hi = sc < 2 ? CTXL : TB;
;         const int pbase = dir == 0 ? 128 * sc : (sc < 2 ? 255 - 128 * sc : 2303 - 128 * (sc - 2));
;     ...
;             float hv = hcar[(sc & 1) * 64 + ch];
;             for (int s = 0; s < seg; ++s) hv = sA[s * 64 + ch] * hv + sB[s * 64 + ch];
; #pragma unroll
;             for (int i = 0; i < 16; ++i) {
;                 const int si = 16 * seg + i; const float a = as[si * 64 + ch], bb = us[si * 64 + ch];
;                 hv = a * hv + bb;
;                 const int p = dir == 0 ? pbase + si : pbase - si;
;                 hout[(size_t)p * D + ch] = f2bf(hv);
;             }
;             if (seg == 7) hcar[((sc + 1) & 1) * 64 + ch] = hv;
	global_load_dwordx2 v[62:63], v[24:25], off
	global_load_dwordx2 v[64:65], v[26:27], off
	global_load_dwordx2 v[66:67], v[28:29], off
	global_load_dwordx2 v[68:69], v[30:31], off
	v_lshl_add_u64 v[24:25], v[56:57], 0, v[0:1]
	v_or_b32_e32 v0, 3, v33
	v_med3_i32 v0, v0, 0, v186
	v_lshlrev_b32_e32 v0, 11, v0
	v_lshl_add_u64 v[26:27], v[56:57], 0, v[0:1]
	v_max_i32_e32 v0, -4, v33
	v_add_u32_e32 v0, 4, v0
	v_min_u32_e32 v0, 0xff, v0
	v_lshlrev_b32_e32 v0, 11, v0
	v_lshl_add_u64 v[28:29], v[56:57], 0, v[0:1]
	global_load_dwordx2 v[70:71], v[24:25], off
	global_load_dwordx2 v[72:73], v[26:27], off
	global_load_dwordx2 v[74:75], v[28:29], off
	s_cmp_lg_u32 s45, 0
	s_cselect_b64 s[92:93], -1, 0
	s_and_b64 s[4:5], s[8:9], exec
	s_mov_b32 s4, 0x1d4c8000
	s_cselect_b32 s4, s4, 0x1f8c8000
	s_add_u32 s4, s30, s4
	s_addc_u32 s5, s31, 0
	s_add_u32 s4, s4, s14
	s_addc_u32 s5, s5, s10
	s_lshl_b32 s10, s39, 7
	s_add_u32 s4, s4, s10
	s_addc_u32 s5, s5, 0
	s_lshl_b32 s10, s26, 4
	v_or_b32_e32 v0, s10, v22
	v_mul_lo_u32 v0, v0, s97
	v_lshl_add_u32 v58, v23, 1, s21
	v_add_u32_e32 v23, s21, v0
	v_lshrrev_b32_e32 v0, 2, v54
	v_and_or_b32 v26, v0, 12, s10
	v_lshlrev_b32_e32 v0, 1, v102
	v_lshl_add_u64 v[60:61], s[4:5], 0, v[0:1]
	v_or_b32_e32 v0, 1, v88
	v_add_u32_e32 v29, -1, v90
	v_cndmask_b32_e64 v0, v29, v0, s[8:9]
	v_lshlrev_b32_e32 v29, 8, v0
	v_mul_lo_u32 v30, v0, s97
	v_or_b32_e32 v0, 2, v88
	v_add_u32_e32 v31, -2, v90
	v_lshlrev_b32_e32 v27, 2, v102
	v_cndmask_b32_e64 v0, v31, v0, s[8:9]
	v_lshlrev_b32_e32 v28, 4, v91
	v_lshlrev_b32_e32 v31, 8, v0
	v_mul_lo_u32 v32, v0, s97
	v_mul_u32_u24_e32 v33, 0x90, v22
	v_lshlrev_b32_e32 v0, 2, v22
	v_lshl_or_b32 v22, v91, 12, v27
	v_add_u32_e32 v96, 0, v22
	v_sub_u32_e32 v22, 0, v28
	v_cndmask_b32_e64 v97, v22, v28, s[8:9]
	v_or_b32_e32 v22, 1, v28
	v_lshl_or_b32 v0, v26, 8, v0
	v_lshl_or_b32 v26, v22, 8, v27
	v_add_u32_e32 v98, 0, v26
	v_sub_u32_e32 v26, 0, v22
	v_cndmask_b32_e64 v99, v26, v22, s[8:9]
	v_or_b32_e32 v22, 2, v28
	v_lshl_or_b32 v26, v22, 8, v27
	v_add_u32_e32 v100, 0, v26
	v_sub_u32_e32 v26, 0, v22
	v_cndmask_b32_e64 v101, v26, v22, s[8:9]
	v_or_b32_e32 v22, 3, v28
	v_lshl_or_b32 v26, v22, 8, v27
	v_add_u32_e32 v103, 0, v26
	v_sub_u32_e32 v26, 0, v22
	v_cndmask_b32_e64 v104, v26, v22, s[8:9]
	v_or_b32_e32 v22, 4, v28
	v_lshl_or_b32 v26, v22, 8, v27
	v_add_u32_e32 v105, 0, v26
	v_sub_u32_e32 v26, 0, v22
	v_cndmask_b32_e64 v106, v26, v22, s[8:9]
	v_or_b32_e32 v22, 5, v28
	v_lshl_or_b32 v26, v22, 8, v27
	v_add_u32_e32 v107, 0, v26
	v_sub_u32_e32 v26, 0, v22
	v_cndmask_b32_e64 v108, v26, v22, s[8:9]
	v_or_b32_e32 v22, 6, v28
	v_lshl_or_b32 v26, v22, 8, v27
	v_add_u32_e32 v109, 0, v26
	v_sub_u32_e32 v26, 0, v22
	v_cndmask_b32_e64 v110, v26, v22, s[8:9]
	v_or_b32_e32 v22, 7, v28
	v_lshl_or_b32 v26, v22, 8, v27
	v_add_u32_e32 v111, 0, v26
	v_sub_u32_e32 v26, 0, v22
	v_cndmask_b32_e64 v112, v26, v22, s[8:9]
	v_or_b32_e32 v22, 8, v28
	v_lshl_or_b32 v26, v22, 8, v27
	v_add_u32_e32 v113, 0, v26
	v_sub_u32_e32 v26, 0, v22
	v_cndmask_b32_e64 v114, v26, v22, s[8:9]
	v_or_b32_e32 v22, 9, v28
	v_lshl_or_b32 v26, v22, 8, v27
	v_add_u32_e32 v115, 0, v26
	v_sub_u32_e32 v26, 0, v22
	v_cndmask_b32_e64 v116, v26, v22, s[8:9]
	v_or_b32_e32 v22, 10, v28
	v_lshl_or_b32 v26, v22, 8, v27
	v_add_u32_e32 v117, 0, v26
	v_sub_u32_e32 v26, 0, v22
	v_cndmask_b32_e64 v118, v26, v22, s[8:9]
	v_or_b32_e32 v22, 11, v28
	v_lshl_or_b32 v26, v22, 8, v27
	v_add_u32_e32 v119, 0, v26
	v_sub_u32_e32 v26, 0, v22
	v_cndmask_b32_e64 v120, v26, v22, s[8:9]
	v_or_b32_e32 v22, 12, v28
	v_lshl_or_b32 v26, v22, 8, v27
	v_add_u32_e32 v121, 0, v26
	v_sub_u32_e32 v26, 0, v22
	v_cndmask_b32_e64 v122, v26, v22, s[8:9]
	v_or_b32_e32 v22, 13, v28
	v_lshl_or_b32 v26, v22, 8, v27
	v_add_u32_e32 v123, 0, v26
	v_sub_u32_e32 v26, 0, v22
	v_cndmask_b32_e64 v124, v26, v22, s[8:9]
	v_or_b32_e32 v22, 14, v28
	v_lshl_or_b32 v26, v22, 8, v27
	v_add_u32_e32 v125, 0, v26
	v_sub_u32_e32 v26, 0, v22
	v_cndmask_b32_e64 v126, v26, v22, s[8:9]
	v_or_b32_e32 v22, 15, v28
	v_and_b32_e32 v24, 48, v54
	v_lshl_or_b32 v26, v22, 8, v27
	v_add_u32_e32 v25, s17, v24
	s_add_i32 s10, 0, 0x1b000
	v_add_u32_e32 v0, 0, v0
	v_add_u32_e32 v127, 0, v26
	v_sub_u32_e32 v26, 0, v22
	v_readlane_b32 s4, v254, 13
	v_add_u32_e32 v92, s10, v27
	v_cmp_lt_i32_e64 s[10:11], 0, v91
	v_add_u32_e32 v93, 64, v0
	v_add_u32_e32 v94, 0x80, v0
	v_add_u32_e32 v95, 0xc0, v0
	v_cndmask_b32_e64 v128, v26, v22, s[8:9]
	v_add_u32_e32 v129, s4, v27
	v_add_u32_e32 v130, v89, v29
	v_add_u32_e32 v131, v58, v30
	v_add_u32_e32 v132, v89, v31
	v_add_u32_e32 v133, v58, v32
	v_add_u32_e32 v134, v23, v24
	v_add_u32_e32 v135, v25, v33
	s_waitcnt vmcnt(0)
	s_branch .LBB0_63

; #define LAS __attribute__((address_space(3)))
; __device__ __forceinline__ unsigned pk2(float lo, float hi) { const f32x2_t v = {lo, hi}; const bf16v2_t b = __builtin_convertvector(v, bf16v2_t); return __builtin_bit_cast(unsigned, b); }
; __device__ __forceinline__ float bflo(unsigned u) { return __uint_as_float(u << 16); }
; __device__ __forceinline__ float bfhi(unsigned u) { return __uint_as_float(u & 0xffff0000u); }
; __device__ __forceinline__ void lru_item(const Args& A, Frame& F, int l, int it) {
;     ...
;         const int lo = sc < 2 ? 0 : CTXL, hi = sc < 2 ? CTXL : TB;
;         const int pbase = dir == 0 ? 128 * sc : (sc < 2 ? 255 - 128 * sc : 2303 - 128 * (sc - 2));
;         {
;             const int pmin = dir == 0 ? pbase + 4 * g4 : pbase - 4 * g4 - 3;
;             f32x4 xw[7];
; #pragma unroll
;             for (int e = 0; e < 7; ++e) {
;                 const int q = pmin - 2 + e;
;                 const float msk = (q >= lo && q < hi) ? 1.f : 0.f;
;                 xw[e][0] = bflo(xr[e].x) * msk; xw[e][1] = bfhi(xr[e].x) * msk; xw[e][2] = bflo(xr[e].y) * msk; xw[e][3] = bfhi(xr[e].y) * msk;
;             }
; #pragma unroll
;             for (int m = 0; m < 4; ++m) {
;                 const f32x4 a = cb + cw[0] * xw[m] + cw[1] * xw[m + 1] + cw[2] * xw[m + 2] + cw[3] * xw[m + 3];
;                 const int si = dir == 0 ? 4 * g4 + m : 4 * g4 + 3 - m;
;                 *(LAS f32x4*)(us + si * 64 + c4) = a;
;                 u32x2 o; o.x = pk2(a[0], a[1]); o.y = pk2(a[2], a[3]);
;                 *(LAS u32x2*)(ub + si * 72 + c4) = o;
;             }
;         }
.LBB0_70:
	v_sub_u32_e32 v24, s39, v88
	s_and_b64 s[4:5], s[4:5], exec
	v_add_u32_e32 v23, s39, v88
	v_add_u32_e32 v24, -3, v24
	s_movk_i32 s4, 0x100
	v_cndmask_b32_e64 v23, v24, v23, s[8:9]
	s_cselect_b32 s25, 0, 0x100
	s_cselect_b32 s52, s4, 0x900
	v_add_u32_e32 v24, -2, v23
	v_cmp_le_i32_e32 vcc, s25, v24
	v_cmp_gt_i32_e64 s[14:15], s52, v24
	s_and_b64 s[4:5], vcc, s[14:15]
	v_cmp_lt_i32_e32 vcc, s25, v23
	v_cmp_ge_i32_e64 s[14:15], s52, v23
	v_cndmask_b32_e64 v24, 0, 1.0, s[4:5]
	s_waitcnt vmcnt(22)
	v_lshlrev_b32_e32 v26, 16, v62
	v_and_b32_e32 v27, 0xffff0000, v62
	v_lshlrev_b32_e32 v28, 16, v63
	v_and_b32_e32 v29, 0xffff0000, v63
	s_and_b64 s[4:5], vcc, s[14:15]
	v_cmp_le_i32_e32 vcc, s25, v23
	v_cmp_gt_i32_e64 s[14:15], s52, v23
	v_pk_mul_f32 v[26:27], v[24:25], v[26:27] op_sel_hi:[0,1]
	v_pk_mul_f32 v[24:25], v[24:25], v[28:29] op_sel_hi:[0,1]
	v_cndmask_b32_e64 v28, 0, 1.0, s[4:5]
	s_waitcnt vmcnt(21)
	v_lshlrev_b32_e32 v30, 16, v64
	v_and_b32_e32 v31, 0xffff0000, v64
	v_lshlrev_b32_e32 v32, 16, v65
	v_and_b32_e32 v33, 0xffff0000, v65
	s_and_b64 s[4:5], vcc, s[14:15]
	v_pk_mul_f32 v[30:31], v[28:29], v[30:31] op_sel_hi:[0,1]
	v_pk_mul_f32 v[28:29], v[28:29], v[32:33] op_sel_hi:[0,1]
	v_cndmask_b32_e64 v32, 0, 1.0, s[4:5]
	s_waitcnt vmcnt(20)
	v_lshlrev_b32_e32 v34, 16, v66
	v_and_b32_e32 v35, 0xffff0000, v66
	v_lshlrev_b32_e32 v36, 16, v67
	v_and_b32_e32 v37, 0xffff0000, v67
	v_pk_mul_f32 v[34:35], v[32:33], v[34:35] op_sel_hi:[0,1]
	v_pk_mul_f32 v[32:33], v[32:33], v[36:37] op_sel_hi:[0,1]
	v_add_u32_e32 v36, 1, v23
	v_cmp_le_i32_e32 vcc, s25, v36
	v_cmp_gt_i32_e64 s[14:15], s52, v36
	s_and_b64 s[4:5], vcc, s[14:15]
	v_cndmask_b32_e64 v36, 0, 1.0, s[4:5]
	s_waitcnt vmcnt(19)
	v_lshlrev_b32_e32 v38, 16, v68
	v_and_b32_e32 v39, 0xffff0000, v68
	v_lshlrev_b32_e32 v40, 16, v69
	v_and_b32_e32 v41, 0xffff0000, v69
	v_pk_mul_f32 v[38:39], v[36:37], v[38:39] op_sel_hi:[0,1]
	v_pk_mul_f32 v[36:37], v[36:37], v[40:41] op_sel_hi:[0,1]
	v_add_u32_e32 v40, 2, v23
	v_cmp_le_i32_e32 vcc, s25, v40
	v_cmp_gt_i32_e64 s[14:15], s52, v40
	s_and_b64 s[4:5], vcc, s[14:15]
	v_cndmask_b32_e64 v40, 0, 1.0, s[4:5]
	s_waitcnt vmcnt(18)
	v_lshlrev_b32_e32 v42, 16, v70
	v_and_b32_e32 v43, 0xffff0000, v70
	v_lshlrev_b32_e32 v44, 16, v71
	v_and_b32_e32 v45, 0xffff0000, v71
	v_pk_mul_f32 v[42:43], v[40:41], v[42:43] op_sel_hi:[0,1]
	v_pk_mul_f32 v[40:41], v[40:41], v[44:45] op_sel_hi:[0,1]
	v_add_u32_e32 v44, 3, v23
	v_cmp_le_i32_e32 vcc, s25, v44
	v_cmp_gt_i32_e64 s[14:15], s52, v44
	v_add_u32_e32 v23, 4, v23
	s_and_b64 s[4:5], vcc, s[14:15]
	v_cmp_le_i32_e32 vcc, s25, v23
	v_cmp_gt_i32_e64 s[14:15], s52, v23
	v_cndmask_b32_e64 v44, 0, 1.0, s[4:5]
	s_waitcnt vmcnt(17)
	v_lshlrev_b32_e32 v46, 16, v72
	v_and_b32_e32 v47, 0xffff0000, v72
	v_lshlrev_b32_e32 v48, 16, v73
	v_and_b32_e32 v49, 0xffff0000, v73
	s_and_b64 s[4:5], vcc, s[14:15]
	v_pk_fma_f32 v[26:27], v[2:3], v[26:27], v[18:19]
	v_pk_fma_f32 v[24:25], v[4:5], v[24:25], v[20:21]
	v_pk_mul_f32 v[46:47], v[44:45], v[46:47] op_sel_hi:[0,1]
	v_pk_mul_f32 v[44:45], v[44:45], v[48:49] op_sel_hi:[0,1]
	v_cndmask_b32_e64 v48, 0, 1.0, s[4:5]
	s_waitcnt vmcnt(16)
	v_lshlrev_b32_e32 v50, 16, v74
	v_and_b32_e32 v51, 0xffff0000, v74
	v_lshlrev_b32_e32 v52, 16, v75
	v_and_b32_e32 v53, 0xffff0000, v75
	v_pk_fma_f32 v[24:25], v[8:9], v[28:29], v[24:25]
	v_pk_fma_f32 v[26:27], v[6:7], v[30:31], v[26:27]
	v_pk_mul_f32 v[50:51], v[48:49], v[50:51] op_sel_hi:[0,1]
	v_pk_mul_f32 v[48:49], v[48:49], v[52:53] op_sel_hi:[0,1]
	v_pk_fma_f32 v[52:53], v[10:11], v[34:35], v[26:27]
	v_pk_fma_f32 v[24:25], v[12:13], v[32:33], v[24:25]
	v_lshl_add_u32 v23, v22, 8, v89
	v_pk_fma_f32 v[26:27], v[16:17], v[36:37], v[24:25]
	v_pk_fma_f32 v[24:25], v[14:15], v[38:39], v[52:53]
	ds_write_b128 v23, v[24:27]
	v_cvt_pk_bf16_f32 v24, v24, v25
	v_cvt_pk_bf16_f32 v25, v26, v27
	v_mad_u64_u32 v[22:23], s[4:5], v22, s97, v[58:59]
	ds_write_b64 v22, v[24:25]
	v_pk_fma_f32 v[22:23], v[2:3], v[30:31], v[18:19]
	v_pk_fma_f32 v[24:25], v[4:5], v[28:29], v[20:21]
	v_pk_fma_f32 v[22:23], v[6:7], v[34:35], v[22:23]
	v_pk_fma_f32 v[24:25], v[8:9], v[32:33], v[24:25]
	v_pk_fma_f32 v[22:23], v[10:11], v[38:39], v[22:23]
	v_pk_fma_f32 v[24:25], v[12:13], v[36:37], v[24:25]
	v_pk_fma_f32 v[22:23], v[14:15], v[42:43], v[22:23]
	v_pk_fma_f32 v[24:25], v[16:17], v[40:41], v[24:25]
	ds_write_b128 v130, v[22:25]
	v_cvt_pk_bf16_f32 v22, v22, v23
	v_cvt_pk_bf16_f32 v23, v24, v25
	ds_write_b64 v131, v[22:23]
	v_pk_fma_f32 v[22:23], v[2:3], v[34:35], v[18:19]
	v_pk_fma_f32 v[24:25], v[4:5], v[32:33], v[20:21]
	v_pk_fma_f32 v[22:23], v[6:7], v[38:39], v[22:23]
	v_pk_fma_f32 v[24:25], v[8:9], v[36:37], v[24:25]
	v_pk_fma_f32 v[22:23], v[10:11], v[42:43], v[22:23]
	v_pk_fma_f32 v[24:25], v[12:13], v[40:41], v[24:25]
	v_pk_fma_f32 v[22:23], v[14:15], v[46:47], v[22:23]
	v_pk_fma_f32 v[24:25], v[16:17], v[44:45], v[24:25]
	ds_write_b128 v132, v[22:25]
	v_cvt_pk_bf16_f32 v22, v22, v23
	v_cvt_pk_bf16_f32 v23, v24, v25
	ds_write_b64 v133, v[22:23]
	v_pk_fma_f32 v[22:23], v[2:3], v[38:39], v[18:19]
	v_pk_fma_f32 v[24:25], v[4:5], v[36:37], v[20:21]
	v_pk_fma_f32 v[22:23], v[6:7], v[42:43], v[22:23]
	v_pk_fma_f32 v[24:25], v[8:9], v[40:41], v[24:25]
	v_pk_fma_f32 v[22:23], v[10:11], v[46:47], v[22:23]
	v_pk_fma_f32 v[24:25], v[12:13], v[44:45], v[24:25]
	v_or_b32_e32 v26, s45, v88
	v_pk_fma_f32 v[24:25], v[16:17], v[48:49], v[24:25]
	v_pk_fma_f32 v[22:23], v[14:15], v[50:51], v[22:23]
	v_lshl_add_u32 v27, v26, 8, v89
	s_add_i32 s45, s2, 1
	ds_write_b128 v27, v[22:25]
	v_cvt_pk_bf16_f32 v22, v22, v23
	v_cvt_pk_bf16_f32 v23, v24, v25
	v_mad_u64_u32 v[24:25], s[4:5], v26, s97, v[58:59]
; #define LAS __attribute__((address_space(3)))
; __device__ __forceinline__ void lru_item(const Args& A, Frame& F, int l, int it) {
;     ...
;             const int sn = sc + 1 < NCH ? sc + 1 : sc;
;             const int lon = sn < 2 ? 0 : CTXL, hin = sn < 2 ? CTXL : TB;
;             const int pbn = dir == 0 ? 128 * sn : (sn < 2 ? 255 - 128 * sn : 2303 - 128 * (sn - 2));
;             const int pminn = dir == 0 ? pbn + 4 * g4 : pbn - 4 * g4 - 3;
; #pragma unroll
;             for (int e = 0; e < 7; ++e) { const int q = pminn - 2 + e; const int qc = q < lon ? lon : (q >= hin ? hin - 1 : q); xr[e] = *(const u32x2*)(lx + (size_t)qc * D); }
;         }
;         __builtin_amdgcn_fence(__ATOMIC_RELEASE, "workgroup"); __builtin_amdgcn_wave_barrier(); __builtin_amdgcn_fence(__ATOMIC_ACQUIRE, "workgroup");
;         {
;             bf16x8 af[2];
; #pragma unroll
;             for (int ks = 0; ks < 2; ++ks) af[ks] = *(const LAS bf16x8*)(ub + (16 * w + fr) * 72 + 32 * ks + 8 * fq);
;             f32x4 gacc[8];
; #pragma unroll
;             for (int nt = 0; nt < 8; ++nt) {
;                 gacc[nt] = (f32x4){0.f, 0.f, 0.f, 0.f};
; #pragma unroll
;                 for (int ks = 0; ks < 2; ++ks) {
;                     const bf16x8 bfm = *(const LAS bf16x8*)(wgs + (16 * nt + fr) * 72 + 32 * ks + 8 * fq);
;                     gacc[nt] = __builtin_amdgcn_mfma_f32_16x16x32_bf16(af[ks], bfm, gacc[nt], 0, 0, 0);
;                 }
;             }
; #pragma unroll
;             for (int nt = 0; nt < 4; ++nt)
; #pragma unroll
;                 for (int r = 0; r < 4; ++r) {
;                     const int si = 16 * w + 4 * fq + r, ch = 16 * nt + fr;
;                     const float d0 = 1.f + __builtin_amdgcn_exp2f(fminf((gacc[nt][r] + bgr[nt]) * -1.4426950408889634f, 60.f));
;                     const float d1 = 1.f + __builtin_amdgcn_exp2f(fminf((gacc[nt + 4][r] + bgi[nt]) * -1.4426950408889634f, 60.f));
;                     const float rr = frcp(d0 * d1);
;                     const float rg = rr * d1, ig = rr * d0;
;                     const float av = __builtin_amdgcn_exp2f(rg * spl[nt]);
;                     const float mult = __builtin_amdgcn_sqrtf(fmaxf(1.f - av * av, 0.f));
;                     const float uu = us[si * 64 + ch];
;                     as[si * 64 + ch] = av;
;                     us[si * 64 + ch] = mult * ig * uu;
;                 }
	s_cmp_lg_u32 s2, 17
	s_cselect_b32 s4, s45, 17
	s_lshl_b32 s14, s4, 7
	s_sub_i32 s5, 0x9ff, s14
	s_cmp_lt_u32 s4, 2
	s_movk_i32 s4, 0x8ff
	s_cselect_b32 s15, 0, 0x100
	s_cselect_b32 s25, 0x7f, s5
	s_cselect_b32 s52, 0xff, s4
	s_and_b64 s[4:5], s[8:9], exec
	s_cselect_b32 s4, s14, s25
	ds_write_b64 v24, v[22:23]
	v_sub_u32_e32 v23, s4, v88
	v_add_u32_e32 v22, s14, v88
	v_add_u32_e32 v23, -3, v23
	v_cndmask_b32_e64 v24, v23, v22, s[8:9]
	v_add_u32_e32 v22, -2, v24
	v_cmp_gt_i32_e32 vcc, s15, v22
	v_min_i32_e32 v22, s52, v22
	v_mov_b32_e32 v25, s15
	v_cndmask_b32_e32 v22, v22, v25, vcc
	v_ashrrev_i32_e32 v23, 31, v22
	v_lshlrev_b64 v[22:23], 11, v[22:23]
	v_lshl_add_u64 v[22:23], v[56:57], 0, v[22:23]
	global_load_dwordx2 v[62:63], v[22:23], off
	v_add_u32_e32 v22, -1, v24
	v_cmp_lt_i32_e32 vcc, s15, v24
	v_min_i32_e32 v22, s52, v22
	s_and_b32 s2, s2, 1
	v_cndmask_b32_e32 v22, v25, v22, vcc
	v_ashrrev_i32_e32 v23, 31, v22
	v_lshlrev_b64 v[22:23], 11, v[22:23]
	v_lshl_add_u64 v[22:23], v[56:57], 0, v[22:23]
	global_load_dwordx2 v[64:65], v[22:23], off
	v_cmp_gt_i32_e32 vcc, s15, v24
	v_min_i32_e32 v22, s52, v24
	s_lshl_b32 s4, s2, 12
	v_cndmask_b32_e32 v22, v22, v25, vcc
	v_ashrrev_i32_e32 v23, 31, v22
	v_lshlrev_b64 v[22:23], 11, v[22:23]
	v_lshl_add_u64 v[22:23], v[56:57], 0, v[22:23]
	global_load_dwordx2 v[66:67], v[22:23], off
	v_add_u32_e32 v22, 1, v24
	v_cmp_gt_i32_e32 vcc, s15, v22
	v_min_i32_e32 v22, s52, v22
	s_add_i32 s4, s4, 0
	v_cndmask_b32_e32 v22, v22, v25, vcc
	v_ashrrev_i32_e32 v23, 31, v22
	v_lshlrev_b64 v[22:23], 11, v[22:23]
	v_lshl_add_u64 v[22:23], v[56:57], 0, v[22:23]
	global_load_dwordx2 v[68:69], v[22:23], off
	v_add_u32_e32 v22, 2, v24
	v_cmp_gt_i32_e32 vcc, s15, v22
	v_min_i32_e32 v22, s52, v22
	s_nop 0
	v_cndmask_b32_e32 v22, v22, v25, vcc
	v_ashrrev_i32_e32 v23, 31, v22
	v_lshlrev_b64 v[22:23], 11, v[22:23]
	v_lshl_add_u64 v[22:23], v[56:57], 0, v[22:23]
	global_load_dwordx2 v[70:71], v[22:23], off
	v_add_u32_e32 v22, 3, v24
	v_cmp_gt_i32_e32 vcc, s15, v22
	v_min_i32_e32 v22, s52, v22
	s_nop 0
	v_cndmask_b32_e32 v22, v22, v25, vcc
	v_ashrrev_i32_e32 v23, 31, v22
	v_lshlrev_b64 v[22:23], 11, v[22:23]
	v_lshl_add_u64 v[22:23], v[56:57], 0, v[22:23]
	global_load_dwordx2 v[72:73], v[22:23], off
	v_add_u32_e32 v22, 4, v24
	v_cmp_gt_i32_e32 vcc, s15, v22
	v_min_i32_e32 v22, s52, v22
	s_nop 0
	v_cndmask_b32_e32 v22, v22, v25, vcc
	v_ashrrev_i32_e32 v23, 31, v22
	v_lshlrev_b64 v[22:23], 11, v[22:23]
	v_lshl_add_u64 v[22:23], v[56:57], 0, v[22:23]
	global_load_dwordx2 v[74:75], v[22:23], off
	s_waitcnt lgkmcnt(0)
	ds_read_b128 v[26:29], v134
	ds_read_b128 v[144:147], v134 offset:64
	ds_read_b128 v[22:25], v135
	ds_read_b128 v[30:33], v135 offset:64
	ds_read_b128 v[34:37], v135 offset:6976
	s_waitcnt lgkmcnt(2)
	v_mfma_f32_16x16x32_bf16 v[22:25], v[26:29], v[22:25], 0
	ds_read_b128 v[42:45], v135 offset:9280
	ds_read_b128 v[148:151], v135 offset:13888
	s_waitcnt lgkmcnt(3)
	v_mfma_f32_16x16x32_bf16 v[46:49], v[144:147], v[30:33], v[22:25]
	ds_read_b128 v[30:33], v135 offset:2368
	s_nop 2
	ds_read_b128 v[22:25], v135 offset:2304
	s_waitcnt lgkmcnt(0)
	v_mfma_f32_16x16x32_bf16 v[22:25], v[26:29], v[22:25], 0
	s_nop 0
	v_add_f32_e32 v46, v55, v46
	v_mul_f32_e32 v46, 0xbfb8aa3b, v46
	v_min_f32_e32 v46, 0x42700000, v46
	v_mfma_f32_16x16x32_bf16 v[38:41], v[144:147], v[30:33], v[22:25]
	ds_read_b128 v[30:33], v135 offset:4672
	v_exp_f32_e32 v46, v46
	v_add_f32_e32 v48, v55, v48
	ds_read_b128 v[22:25], v135 offset:4608
	s_waitcnt lgkmcnt(0)
	v_mfma_f32_16x16x32_bf16 v[22:25], v[26:29], v[22:25], 0
	v_add_f32_e32 v46, 1.0, v46
	v_mul_f32_e32 v48, 0xbfb8aa3b, v48
	v_min_f32_e32 v48, 0x42700000, v48
	v_mfma_f32_16x16x32_bf16 v[30:33], v[144:147], v[30:33], v[22:25]
	v_exp_f32_e32 v48, v48
	v_add_f32_e32 v38, v59, v38
	v_mul_f32_e32 v38, 0xbfb8aa3b, v38
	s_nop 0
	ds_read_b128 v[22:25], v135 offset:6912
	s_waitcnt lgkmcnt(0)
	v_mfma_f32_16x16x32_bf16 v[22:25], v[26:29], v[22:25], 0
	v_add_f32_e32 v48, 1.0, v48
	v_min_f32_e32 v38, 0x42700000, v38
	v_exp_f32_e32 v38, v38
	v_mfma_f32_16x16x32_bf16 v[22:25], v[144:147], v[34:37], v[22:25]
	ds_read_b128 v[34:37], v135 offset:9216
	v_add_f32_e32 v40, v59, v40
	v_add_f32_e32 v38, 1.0, v38
	s_waitcnt lgkmcnt(0)
	v_mfma_f32_16x16x32_bf16 v[34:37], v[26:29], v[34:37], 0
	v_mul_f32_e32 v40, 0xbfb8aa3b, v40
	v_min_f32_e32 v40, 0x42700000, v40
	v_exp_f32_e32 v40, v40
	v_mfma_f32_16x16x32_bf16 v[50:53], v[144:147], v[42:45], v[34:37]
	ds_read_b128 v[42:45], v135 offset:11584
	v_add_f32_e32 v30, v78, v30
	v_add_f32_e32 v40, 1.0, v40
	s_nop 0
	ds_read_b128 v[34:37], v135 offset:11520
	s_waitcnt lgkmcnt(0)
	v_mfma_f32_16x16x32_bf16 v[34:37], v[26:29], v[34:37], 0
	s_nop 0
	v_add_f32_e32 v50, v83, v50
	v_mul_f32_e32 v50, 0xbfb8aa3b, v50
	v_min_f32_e32 v50, 0x42700000, v50
	v_exp_f32_e32 v50, v50
	v_mfma_f32_16x16x32_bf16 v[42:45], v[144:147], v[42:45], v[34:37]
	v_mul_f32_e32 v30, 0xbfb8aa3b, v30
	v_min_f32_e32 v30, 0x42700000, v30
	v_add_f32_e32 v50, 1.0, v50
	v_mul_f32_e32 v76, v46, v50
	v_rcp_f32_e32 v76, v76
	ds_read_b128 v[34:37], v135 offset:13824
	s_waitcnt lgkmcnt(0)
	v_mfma_f32_16x16x32_bf16 v[34:37], v[26:29], v[34:37], 0
	v_mul_f32_e32 v50, v50, v76
	v_mul_f32_e32 v50, v80, v50
	v_exp_f32_e32 v50, v50
	v_mul_f32_e32 v46, v46, v76
	v_mfma_f32_16x16x32_bf16 v[34:37], v[144:147], v[148:151], v[34:37]
	ds_read_b128 v[148:151], v135 offset:16128
	v_fma_f32 v76, -v50, v50, 1.0
	v_max_f32_e32 v76, 0, v76
	v_sqrt_f32_e32 v136, v76
	ds_read2_b32 v[76:77], v0 offset1:16
	s_waitcnt lgkmcnt(1)
	v_mfma_f32_16x16x32_bf16 v[26:29], v[26:29], v[148:151], 0
	ds_read_b128 v[148:151], v135 offset:16192
	v_mul_f32_e32 v46, v46, v136
	ds_write_b32 v0, v50 offset:32768
	s_waitcnt lgkmcnt(2)
; __device__ __forceinline__ float frcp(float x) { return __builtin_amdgcn_rcpf(x); }
; __device__ __forceinline__ void lru_item(const Args& A, Frame& F, int l, int it) {
;     ...
; #pragma unroll
;             for (int nt = 0; nt < 4; ++nt)
; #pragma unroll
;                 for (int r = 0; r < 4; ++r) {
;                     const int si = 16 * w + 4 * fq + r, ch = 16 * nt + fr;
;                     const float d0 = 1.f + __builtin_amdgcn_exp2f(fminf((gacc[nt][r] + bgr[nt]) * -1.4426950408889634f, 60.f));
;                     const float d1 = 1.f + __builtin_amdgcn_exp2f(fminf((gacc[nt + 4][r] + bgi[nt]) * -1.4426950408889634f, 60.f));
;                     const float rr = frcp(d0 * d1);
;                     const float rg = rr * d1, ig = rr * d0;
;                     const float av = __builtin_amdgcn_exp2f(rg * spl[nt]);
;                     const float mult = __builtin_amdgcn_sqrtf(fmaxf(1.f - av * av, 0.f));
;                     const float uu = us[si * 64 + ch];
;                     as[si * 64 + ch] = av;
;                     us[si * 64 + ch] = mult * ig * uu;
;                 }
	v_mul_f32_e32 v46, v76, v46
	ds_write_b32 v0, v46
	v_add_f32_e32 v46, v55, v47
	v_add_f32_e32 v47, v83, v51
	v_mul_f32_e32 v46, 0xbfb8aa3b, v46
	v_mul_f32_e32 v47, 0xbfb8aa3b, v47
	v_min_f32_e32 v46, 0x42700000, v46
	v_min_f32_e32 v47, 0x42700000, v47
	v_exp_f32_e32 v46, v46
	v_exp_f32_e32 v47, v47
	v_add_f32_e32 v42, v84, v42
	v_mul_f32_e32 v42, 0xbfb8aa3b, v42
	v_add_f32_e32 v46, 1.0, v46
	v_add_f32_e32 v47, 1.0, v47
	v_mul_f32_e32 v50, v46, v47
	v_rcp_f32_e32 v50, v50
	v_min_f32_e32 v42, 0x42700000, v42
	v_exp_f32_e32 v42, v42
	v_add_f32_e32 v34, v85, v34
	v_mul_f32_e32 v47, v47, v50
	v_mul_f32_e32 v50, v46, v50
	v_mul_f32_e32 v46, v80, v47
	v_exp_f32_e32 v51, v46
	v_add_f32_e32 v42, 1.0, v42
	v_mul_f32_e32 v34, 0xbfb8aa3b, v34
	v_min_f32_e32 v34, 0x42700000, v34
	v_fma_f32 v46, -v51, v51, 1.0
	v_max_f32_e32 v46, 0, v46
	v_sqrt_f32_e32 v76, v46
	ds_read2st64_b32 v[46:47], v0 offset0:1 offset1:2
	v_exp_f32_e32 v30, v30
	v_exp_f32_e32 v34, v34
	v_mul_f32_e32 v50, v50, v76
	v_add_f32_e32 v32, v78, v32
	s_waitcnt lgkmcnt(0)
	v_mul_f32_e32 v46, v46, v50
	v_add_f32_e32 v50, v83, v52
	v_mul_f32_e32 v50, 0xbfb8aa3b, v50
	v_min_f32_e32 v50, 0x42700000, v50
	v_exp_f32_e32 v50, v50
	v_add_f32_e32 v30, 1.0, v30
	v_add_f32_e32 v34, 1.0, v34
	v_mul_f32_e32 v32, 0xbfb8aa3b, v32
	v_add_f32_e32 v50, 1.0, v50
	v_mul_f32_e32 v52, v48, v50
	v_rcp_f32_e32 v52, v52
	v_min_f32_e32 v32, 0x42700000, v32
	v_exp_f32_e32 v32, v32
	v_mfma_f32_16x16x32_bf16 v[26:29], v[144:147], v[148:151], v[26:29]
	v_mul_f32_e32 v50, v50, v52
	v_mul_f32_e32 v50, v80, v50
	v_exp_f32_e32 v50, v50
	v_mul_f32_e32 v48, v48, v52
	v_add_f32_e32 v32, 1.0, v32
	v_add_f32_e32 v22, v79, v22
	v_fma_f32 v52, -v50, v50, 1.0
	v_max_f32_e32 v52, 0, v52
	v_sqrt_f32_e32 v52, v52
	ds_write2st64_b32 v0, v51, v50 offset0:129 offset1:130
	v_add_f32_e32 v26, v86, v26
	v_mul_f32_e32 v22, 0xbfb8aa3b, v22
	v_mul_f32_e32 v48, v48, v52
	v_mul_f32_e32 v47, v48, v47
	ds_write2st64_b32 v0, v46, v47 offset0:1 offset1:2
	v_add_f32_e32 v46, v55, v49
	v_add_f32_e32 v47, v83, v53
	v_mul_f32_e32 v46, 0xbfb8aa3b, v46
	v_mul_f32_e32 v47, 0xbfb8aa3b, v47
	v_min_f32_e32 v46, 0x42700000, v46
	v_min_f32_e32 v47, 0x42700000, v47
	v_exp_f32_e32 v46, v46
	v_exp_f32_e32 v47, v47
	ds_read_b32 v49, v0 offset:768
	v_mul_f32_e32 v26, 0xbfb8aa3b, v26
	v_add_f32_e32 v46, 1.0, v46
	v_add_f32_e32 v47, 1.0, v47
	v_mul_f32_e32 v48, v46, v47
	v_rcp_f32_e32 v48, v48
	v_min_f32_e32 v22, 0x42700000, v22
	v_min_f32_e32 v26, 0x42700000, v26
	v_exp_f32_e32 v22, v22
	v_mul_f32_e32 v47, v47, v48
	v_mul_f32_e32 v47, v80, v47
	v_exp_f32_e32 v47, v47
	v_mul_f32_e32 v46, v46, v48
	v_exp_f32_e32 v26, v26
	v_add_f32_e32 v22, 1.0, v22
	v_fma_f32 v48, -v47, v47, 1.0
	v_max_f32_e32 v48, 0, v48
	v_sqrt_f32_e32 v48, v48
	ds_write_b32 v0, v47 offset:33536
	v_add_f32_e32 v26, 1.0, v26
	v_add_f32_e32 v24, v79, v24
	v_mul_f32_e32 v46, v46, v48
	s_waitcnt lgkmcnt(1)
	v_mul_f32_e32 v46, v46, v49
	ds_write_b32 v0, v46 offset:768
	v_mul_f32_e32 v46, v38, v42
	v_rcp_f32_e32 v46, v46
	v_mul_f32_e32 v24, 0xbfb8aa3b, v24
	v_min_f32_e32 v24, 0x42700000, v24
	v_exp_f32_e32 v24, v24
	v_mul_f32_e32 v42, v42, v46
	v_mul_f32_e32 v42, v81, v42
	v_exp_f32_e32 v42, v42
	v_mul_f32_e32 v38, v38, v46
	v_add_f32_e32 v24, 1.0, v24
	v_fma_f32 v46, -v42, v42, 1.0
	v_max_f32_e32 v46, 0, v46
	v_sqrt_f32_e32 v46, v46
	ds_write_b32 v0, v42 offset:32832
	v_mul_f32_e32 v38, v38, v46
	v_mul_f32_e32 v38, v38, v77
	ds_write_b32 v0, v38 offset:64
	v_add_f32_e32 v38, v59, v39
	v_add_f32_e32 v39, v84, v43
	v_mul_f32_e32 v38, 0xbfb8aa3b, v38
	v_mul_f32_e32 v39, 0xbfb8aa3b, v39
	v_min_f32_e32 v38, 0x42700000, v38
	v_min_f32_e32 v39, 0x42700000, v39
	v_exp_f32_e32 v38, v38
	v_exp_f32_e32 v39, v39
	v_add_f32_e32 v38, 1.0, v38
	v_add_f32_e32 v39, 1.0, v39
	v_mul_f32_e32 v42, v38, v39
	v_rcp_f32_e32 v42, v42
	s_nop 0
	v_mul_f32_e32 v39, v39, v42
	v_mul_f32_e32 v42, v38, v42
	v_mul_f32_e32 v38, v81, v39
	v_exp_f32_e32 v43, v38
	s_nop 0
	v_fma_f32 v38, -v43, v43, 1.0
	v_max_f32_e32 v38, 0, v38
	v_sqrt_f32_e32 v46, v38
	ds_read2st64_b32 v[38:39], v93 offset0:1 offset1:2
	v_mul_f32_e32 v42, v42, v46
	s_waitcnt lgkmcnt(0)
	v_mul_f32_e32 v38, v42, v38
	v_add_f32_e32 v42, v84, v44
	v_mul_f32_e32 v42, 0xbfb8aa3b, v42
	v_min_f32_e32 v42, 0x42700000, v42
	v_exp_f32_e32 v42, v42
	s_nop 0
	v_add_f32_e32 v42, 1.0, v42
	v_mul_f32_e32 v44, v40, v42
	v_rcp_f32_e32 v44, v44
	s_nop 0
	v_mul_f32_e32 v42, v42, v44
	v_mul_f32_e32 v42, v81, v42
	v_exp_f32_e32 v42, v42
	v_mul_f32_e32 v40, v40, v44
	v_fma_f32 v44, -v42, v42, 1.0
	v_max_f32_e32 v44, 0, v44
	v_sqrt_f32_e32 v44, v44
	s_nop 0
	v_mul_f32_e32 v40, v40, v44
	v_mul_f32_e32 v39, v40, v39
	ds_write2st64_b32 v93, v38, v39 offset0:1 offset1:2
	v_add_f32_e32 v38, v59, v41
	v_add_f32_e32 v39, v84, v45
	v_mul_f32_e32 v38, 0xbfb8aa3b, v38
	v_mul_f32_e32 v39, 0xbfb8aa3b, v39
	v_min_f32_e32 v38, 0x42700000, v38
	v_min_f32_e32 v39, 0x42700000, v39
	v_exp_f32_e32 v38, v38
	v_exp_f32_e32 v39, v39
	ds_read_b32 v41, v93 offset:768
	v_add_f32_e32 v38, 1.0, v38
	v_add_f32_e32 v39, 1.0, v39
	v_mul_f32_e32 v40, v38, v39
	v_rcp_f32_e32 v40, v40
	s_nop 0
	v_mul_f32_e32 v39, v39, v40
	v_mul_f32_e32 v39, v81, v39
	v_exp_f32_e32 v39, v39
	v_mul_f32_e32 v38, v38, v40
	v_fma_f32 v40, -v39, v39, 1.0
	v_max_f32_e32 v40, 0, v40
	v_sqrt_f32_e32 v40, v40
	ds_write2st64_b32 v93, v42, v39 offset0:130 offset1:131
	v_mul_f32_e32 v38, v38, v40
	s_waitcnt lgkmcnt(1)
	v_mul_f32_e32 v38, v38, v41
	ds_write2st64_b32 v93, v38, v43 offset0:3 offset1:129
	v_mul_f32_e32 v38, v30, v34
	v_rcp_f32_e32 v38, v38
	ds_read_b32 v39, v0 offset:128
	v_mul_f32_e32 v34, v34, v38
	v_mul_f32_e32 v34, v82, v34
	v_exp_f32_e32 v34, v34
	v_mul_f32_e32 v30, v30, v38
	v_fma_f32 v38, -v34, v34, 1.0
	v_max_f32_e32 v38, 0, v38
	v_sqrt_f32_e32 v38, v38
	ds_write_b32 v0, v34 offset:32896
	v_mul_f32_e32 v30, v30, v38
	s_waitcnt lgkmcnt(1)
; #define LAS __attribute__((address_space(3)))
; __device__ __forceinline__ float frcp(float x) { return __builtin_amdgcn_rcpf(x); }
; __device__ __forceinline__ void lru_item(const Args& A, Frame& F, int l, int it) {
;     ...
; #pragma unroll
;             for (int nt = 0; nt < 4; ++nt)
; #pragma unroll
;                 for (int r = 0; r < 4; ++r) {
;                     const int si = 16 * w + 4 * fq + r, ch = 16 * nt + fr;
;                     const float d0 = 1.f + __builtin_amdgcn_exp2f(fminf((gacc[nt][r] + bgr[nt]) * -1.4426950408889634f, 60.f));
;                     const float d1 = 1.f + __builtin_amdgcn_exp2f(fminf((gacc[nt + 4][r] + bgi[nt]) * -1.4426950408889634f, 60.f));
;                     const float rr = frcp(d0 * d1);
;                     const float rg = rr * d1, ig = rr * d0;
;                     const float av = __builtin_amdgcn_exp2f(rg * spl[nt]);
;                     const float mult = __builtin_amdgcn_sqrtf(fmaxf(1.f - av * av, 0.f));
;                     const float uu = us[si * 64 + ch];
;                     as[si * 64 + ch] = av;
;                     us[si * 64 + ch] = mult * ig * uu;
;                 }
;         }
;         __builtin_amdgcn_fence(__ATOMIC_RELEASE, "workgroup"); __builtin_amdgcn_wave_barrier(); __builtin_amdgcn_fence(__ATOMIC_ACQUIRE, "workgroup");
;         {
;             const int ch = tid & 63, seg = tid >> 6;
;             float A = 1.f, Bv = 0.f;
; #pragma unroll
;             for (int i = 0; i < 16; ++i) { const int si = 16 * seg + i; const float a = as[si * 64 + ch], bb = us[si * 64 + ch]; A *= a; Bv = a * Bv + bb; }
;             LAS float* sA = segA + (sc & 1) * 1024; LAS float* sB = segB + (sc & 1) * 1024;
;             sA[seg * 64 + ch] = A; sB[seg * 64 + ch] = Bv;
;             __syncthreads();
	v_mul_f32_e32 v30, v30, v39
	ds_write_b32 v0, v30 offset:128
	v_add_f32_e32 v30, v78, v31
	v_add_f32_e32 v31, v85, v35
	v_mul_f32_e32 v30, 0xbfb8aa3b, v30
	v_mul_f32_e32 v31, 0xbfb8aa3b, v31
	v_min_f32_e32 v30, 0x42700000, v30
	v_min_f32_e32 v31, 0x42700000, v31
	v_exp_f32_e32 v30, v30
	v_exp_f32_e32 v31, v31
	v_add_f32_e32 v30, 1.0, v30
	v_add_f32_e32 v31, 1.0, v31
	v_mul_f32_e32 v34, v30, v31
	v_rcp_f32_e32 v34, v34
	s_nop 0
	v_mul_f32_e32 v31, v31, v34
	v_mul_f32_e32 v34, v30, v34
	v_mul_f32_e32 v30, v82, v31
	v_exp_f32_e32 v35, v30
	s_nop 0
	v_fma_f32 v30, -v35, v35, 1.0
	v_max_f32_e32 v30, 0, v30
	v_sqrt_f32_e32 v38, v30
	ds_read2st64_b32 v[30:31], v94 offset0:1 offset1:2
	v_mul_f32_e32 v34, v34, v38
	s_waitcnt lgkmcnt(0)
	v_mul_f32_e32 v30, v34, v30
	v_add_f32_e32 v34, v85, v36
	v_mul_f32_e32 v34, 0xbfb8aa3b, v34
	v_min_f32_e32 v34, 0x42700000, v34
	v_exp_f32_e32 v34, v34
	s_nop 0
	v_add_f32_e32 v34, 1.0, v34
	v_mul_f32_e32 v36, v32, v34
	v_rcp_f32_e32 v36, v36
	s_nop 0
	v_mul_f32_e32 v34, v34, v36
	v_mul_f32_e32 v34, v82, v34
	v_exp_f32_e32 v34, v34
	v_mul_f32_e32 v32, v32, v36
	v_fma_f32 v36, -v34, v34, 1.0
	v_max_f32_e32 v36, 0, v36
	v_sqrt_f32_e32 v36, v36
	s_nop 0
	v_mul_f32_e32 v32, v32, v36
	v_mul_f32_e32 v31, v32, v31
	ds_write2st64_b32 v94, v30, v31 offset0:1 offset1:2
	v_add_f32_e32 v30, v78, v33
	v_add_f32_e32 v31, v85, v37
	v_mul_f32_e32 v30, 0xbfb8aa3b, v30
	v_mul_f32_e32 v31, 0xbfb8aa3b, v31
	v_min_f32_e32 v30, 0x42700000, v30
	v_min_f32_e32 v31, 0x42700000, v31
	v_exp_f32_e32 v30, v30
	v_exp_f32_e32 v31, v31
	ds_read_b32 v33, v94 offset:768
	v_add_f32_e32 v30, 1.0, v30
	v_add_f32_e32 v31, 1.0, v31
	v_mul_f32_e32 v32, v30, v31
	v_rcp_f32_e32 v32, v32
	s_nop 0
	v_mul_f32_e32 v31, v31, v32
	v_mul_f32_e32 v31, v82, v31
	v_exp_f32_e32 v31, v31
	v_mul_f32_e32 v30, v30, v32
	v_fma_f32 v32, -v31, v31, 1.0
	v_max_f32_e32 v32, 0, v32
	v_sqrt_f32_e32 v32, v32
	ds_write2st64_b32 v94, v34, v31 offset0:130 offset1:131
	v_mul_f32_e32 v30, v30, v32
	s_waitcnt lgkmcnt(1)
	v_mul_f32_e32 v30, v30, v33
	ds_write2st64_b32 v94, v30, v35 offset0:3 offset1:129
	v_mul_f32_e32 v30, v22, v26
	v_rcp_f32_e32 v30, v30
	ds_read_b32 v31, v0 offset:192
	v_mul_f32_e32 v26, v26, v30
	v_mul_f32_e32 v26, v87, v26
	v_exp_f32_e32 v26, v26
	v_mul_f32_e32 v22, v22, v30
	v_fma_f32 v30, -v26, v26, 1.0
	v_max_f32_e32 v30, 0, v30
	v_sqrt_f32_e32 v30, v30
	ds_write_b32 v0, v26 offset:32960
	v_mul_f32_e32 v22, v22, v30
	s_waitcnt lgkmcnt(1)
	v_mul_f32_e32 v22, v22, v31
	ds_write_b32 v0, v22 offset:192
	v_add_f32_e32 v22, v79, v23
	v_add_f32_e32 v23, v86, v27
	v_mul_f32_e32 v22, 0xbfb8aa3b, v22
	v_mul_f32_e32 v23, 0xbfb8aa3b, v23
	v_min_f32_e32 v22, 0x42700000, v22
	v_min_f32_e32 v23, 0x42700000, v23
	v_exp_f32_e32 v22, v22
	v_exp_f32_e32 v23, v23
	v_add_f32_e32 v22, 1.0, v22
	v_add_f32_e32 v23, 1.0, v23
	v_mul_f32_e32 v26, v22, v23
	v_rcp_f32_e32 v26, v26
	s_nop 0
	v_mul_f32_e32 v23, v23, v26
	v_mul_f32_e32 v26, v22, v26
	v_mul_f32_e32 v22, v87, v23
	v_exp_f32_e32 v27, v22
	s_nop 0
	v_fma_f32 v22, -v27, v27, 1.0
	v_max_f32_e32 v22, 0, v22
	v_sqrt_f32_e32 v30, v22
	ds_read2st64_b32 v[22:23], v95 offset0:1 offset1:2
	v_mul_f32_e32 v26, v26, v30
	s_waitcnt lgkmcnt(0)
	v_mul_f32_e32 v22, v26, v22
	v_add_f32_e32 v26, v86, v28
	v_mul_f32_e32 v26, 0xbfb8aa3b, v26
	v_min_f32_e32 v26, 0x42700000, v26
	v_exp_f32_e32 v26, v26
	s_nop 0
	v_add_f32_e32 v26, 1.0, v26
	v_mul_f32_e32 v28, v24, v26
	v_rcp_f32_e32 v28, v28
	s_nop 0
	v_mul_f32_e32 v26, v26, v28
	v_mul_f32_e32 v26, v87, v26
	v_exp_f32_e32 v26, v26
	v_mul_f32_e32 v24, v24, v28
	v_fma_f32 v28, -v26, v26, 1.0
	v_max_f32_e32 v28, 0, v28
	v_sqrt_f32_e32 v28, v28
	s_nop 0
	v_mul_f32_e32 v24, v24, v28
	v_mul_f32_e32 v23, v24, v23
	ds_write2st64_b32 v95, v22, v23 offset0:1 offset1:2
	v_add_f32_e32 v22, v79, v25
	v_add_f32_e32 v23, v86, v29
	v_mul_f32_e32 v22, 0xbfb8aa3b, v22
	v_mul_f32_e32 v23, 0xbfb8aa3b, v23
	v_min_f32_e32 v22, 0x42700000, v22
	v_min_f32_e32 v23, 0x42700000, v23
	v_exp_f32_e32 v22, v22
	v_exp_f32_e32 v23, v23
	ds_read_b32 v25, v95 offset:768
	v_add_f32_e32 v22, 1.0, v22
	v_add_f32_e32 v23, 1.0, v23
	v_mul_f32_e32 v24, v22, v23
	v_rcp_f32_e32 v24, v24
	s_nop 0
	v_mul_f32_e32 v23, v23, v24
	v_mul_f32_e32 v23, v87, v23
	v_exp_f32_e32 v23, v23
	v_mul_f32_e32 v22, v22, v24
	v_fma_f32 v24, -v23, v23, 1.0
	v_max_f32_e32 v24, 0, v24
	v_sqrt_f32_e32 v24, v24
	ds_write2st64_b32 v95, v26, v23 offset0:130 offset1:131
	v_mul_f32_e32 v22, v22, v24
	s_waitcnt lgkmcnt(1)
	v_mul_f32_e32 v22, v22, v25
	ds_write2st64_b32 v95, v22, v27 offset0:3 offset1:129
	s_waitcnt lgkmcnt(0)
	ds_read2st64_b32 v[190:191], v96 offset0:128 offset1:129
	ds_read2st64_b32 v[206:207], v96 offset1:1
	ds_read2st64_b32 v[192:193], v96 offset0:130 offset1:131
	ds_read2st64_b32 v[208:209], v96 offset0:2 offset1:3
	ds_read2st64_b32 v[194:195], v96 offset0:132 offset1:133
	ds_read2st64_b32 v[210:211], v96 offset0:4 offset1:5
	ds_read2st64_b32 v[196:197], v96 offset0:134 offset1:135
	ds_read2st64_b32 v[212:213], v96 offset0:6 offset1:7
	ds_read2st64_b32 v[198:199], v96 offset0:136 offset1:137
	ds_read2st64_b32 v[214:215], v96 offset0:8 offset1:9
	ds_read2st64_b32 v[200:201], v96 offset0:138 offset1:139
	ds_read2st64_b32 v[216:217], v96 offset0:10 offset1:11
	ds_read2st64_b32 v[202:203], v96 offset0:140 offset1:141
	ds_read2st64_b32 v[218:219], v96 offset0:12 offset1:13
	s_waitcnt lgkmcnt(12)
	v_mul_f32_e32 v237, v190, v191
	v_fma_f32 v238, 0, v190, v206
	v_fma_f32 v238, v238, v191, v207
	ds_read2st64_b32 v[204:205], v96 offset0:142 offset1:143
	ds_read2st64_b32 v[220:221], v96 offset0:14 offset1:15
	s_waitcnt lgkmcnt(12)
	v_mul_f32_e32 v237, v237, v192
	v_fma_f32 v238, v238, v192, v208
	v_mul_f32_e32 v237, v237, v193
	v_fma_f32 v238, v238, v193, v209
	s_waitcnt lgkmcnt(10)
	v_mul_f32_e32 v237, v237, v194
	v_fma_f32 v238, v238, v194, v210
	v_mul_f32_e32 v237, v237, v195
	v_fma_f32 v238, v238, v195, v211
	s_waitcnt lgkmcnt(8)
	v_mul_f32_e32 v237, v237, v196
	v_fma_f32 v238, v238, v196, v212
	v_mul_f32_e32 v237, v237, v197
	v_fma_f32 v238, v238, v197, v213
	s_waitcnt lgkmcnt(6)
	v_mul_f32_e32 v237, v237, v198
	v_fma_f32 v238, v238, v198, v214
	v_mul_f32_e32 v237, v237, v199
	v_fma_f32 v238, v238, v199, v215
	s_waitcnt lgkmcnt(4)
	v_mul_f32_e32 v237, v237, v200
	v_fma_f32 v238, v238, v200, v216
	v_mul_f32_e32 v237, v237, v201
	v_fma_f32 v238, v238, v201, v217
	s_waitcnt lgkmcnt(2)
	v_mul_f32_e32 v237, v237, v202
	v_fma_f32 v238, v238, v202, v218
	v_mul_f32_e32 v237, v237, v203
	v_fma_f32 v238, v238, v203, v219
	s_waitcnt lgkmcnt(0)
	v_mul_f32_e32 v237, v237, v204
	v_fma_f32 v238, v238, v204, v220
	v_mul_f32_e32 v237, v237, v205
	v_fma_f32 v238, v238, v205, v221
	v_lshl_add_u32 v22, v54, 2, s4
	v_add_u32_e32 v23, 0x19000, v22
	v_add_u32_e32 v22, 0x19800, v22
	ds_write_b32 v22, v238
	v_lshl_add_u32 v22, s2, 8, v92
	ds_write_b32 v23, v237
	v_readfirstlane_b32 s98, v91
	s_waitcnt lgkmcnt(0)
	s_barrier
; __device__ __forceinline__ bf16_t f2bf(float f) { return (bf16_t)(pk2(f, 0.f) & 0xffffu); }
; __device__ __forceinline__ void lru_item(const Args& A, Frame& F, int l, int it) {
;     ...
;             float hv = hcar[(sc & 1) * 64 + ch];
;             for (int s = 0; s < seg; ++s) hv = sA[s * 64 + ch] * hv + sB[s * 64 + ch];
; #pragma unroll
;             for (int i = 0; i < 16; ++i) {
;                 const int si = 16 * seg + i; const float a = as[si * 64 + ch], bb = us[si * 64 + ch];
;                 hv = a * hv + bb;
;                 const int p = dir == 0 ? pbase + si : pbase - si;
;                 hout[(size_t)p * D + ch] = f2bf(hv);
;             }
;             if (seg == 7) hcar[((sc + 1) & 1) * 64 + ch] = hv;
	ds_read_b32 v22, v22
	v_cndmask_b32_e64 v23, 0, 1, s[78:79]
	v_lshl_add_u32 v23, v23, 12, v129
	v_add_u32_e32 v23, 0xfffff800, v23
	ds_read2st64_b32 v[222:223], v23 offset1:8
	ds_read2st64_b32 v[224:225], v23 offset0:1 offset1:9
	ds_read2st64_b32 v[226:227], v23 offset0:2 offset1:10
	ds_read2st64_b32 v[228:229], v23 offset0:3 offset1:11
	ds_read2st64_b32 v[230:231], v23 offset0:4 offset1:12
	ds_read2st64_b32 v[232:233], v23 offset0:5 offset1:13
	ds_read2st64_b32 v[234:235], v23 offset0:6 offset1:14
	s_waitcnt lgkmcnt(7)
	s_cmp_lt_u32 s98, 1
	s_cbranch_scc1 .Lmy_lru_comb_done
	s_waitcnt lgkmcnt(6)
	v_fma_f32 v22, v22, v222, v223
	s_cmp_lt_u32 s98, 2
	s_cbranch_scc1 .Lmy_lru_comb_done
	s_waitcnt lgkmcnt(5)
	v_fma_f32 v22, v22, v224, v225
	s_cmp_lt_u32 s98, 3
	s_cbranch_scc1 .Lmy_lru_comb_done
	s_waitcnt lgkmcnt(4)
	v_fma_f32 v22, v22, v226, v227
	s_cmp_lt_u32 s98, 4
	s_cbranch_scc1 .Lmy_lru_comb_done
	s_waitcnt lgkmcnt(3)
	v_fma_f32 v22, v22, v228, v229
	s_cmp_lt_u32 s98, 5
	s_cbranch_scc1 .Lmy_lru_comb_done
	s_waitcnt lgkmcnt(2)
	v_fma_f32 v22, v22, v230, v231
	s_cmp_lt_u32 s98, 6
	s_cbranch_scc1 .Lmy_lru_comb_done
	s_waitcnt lgkmcnt(1)
	v_fma_f32 v22, v22, v232, v233
	s_cmp_lt_u32 s98, 7
	s_cbranch_scc1 .Lmy_lru_comb_done
	s_waitcnt lgkmcnt(0)
	v_fma_f32 v22, v22, v234, v235
.Lmy_lru_comb_done:
	v_fma_f32 v22, v22, v190, v206
	v_add_u32_e32 v24, s39, v97
	v_ashrrev_i32_e32 v25, 31, v24
	v_lshlrev_b64 v[24:25], 11, v[24:25]
	v_cvt_pk_bf16_f32 v23, v22, s0
	v_lshl_add_u64 v[24:25], v[60:61], 0, v[24:25]
	global_store_short v[24:25], v23, off
	v_fma_f32 v22, v22, v191, v207
	v_add_u32_e32 v240, s39, v99
	v_ashrrev_i32_e32 v241, 31, v240
	v_lshlrev_b64 v[240:241], 11, v[240:241]
	v_cvt_pk_bf16_f32 v239, v22, s0
	v_lshl_add_u64 v[240:241], v[60:61], 0, v[240:241]
	global_store_short v[240:241], v239, off
	v_fma_f32 v22, v22, v192, v208
	v_add_u32_e32 v24, s39, v101
	v_ashrrev_i32_e32 v25, 31, v24
	v_lshlrev_b64 v[24:25], 11, v[24:25]
	v_cvt_pk_bf16_f32 v23, v22, s0
	v_lshl_add_u64 v[24:25], v[60:61], 0, v[24:25]
	global_store_short v[24:25], v23, off
	v_fma_f32 v22, v22, v193, v209
	v_add_u32_e32 v240, s39, v104
	v_ashrrev_i32_e32 v241, 31, v240
	v_lshlrev_b64 v[240:241], 11, v[240:241]
	v_cvt_pk_bf16_f32 v239, v22, s0
	v_lshl_add_u64 v[240:241], v[60:61], 0, v[240:241]
	global_store_short v[240:241], v239, off
	v_fma_f32 v22, v22, v194, v210
	v_add_u32_e32 v24, s39, v106
	v_ashrrev_i32_e32 v25, 31, v24
	v_lshlrev_b64 v[24:25], 11, v[24:25]
	v_cvt_pk_bf16_f32 v23, v22, s0
	v_lshl_add_u64 v[24:25], v[60:61], 0, v[24:25]
	global_store_short v[24:25], v23, off
	v_fma_f32 v22, v22, v195, v211
	v_add_u32_e32 v240, s39, v108
	v_ashrrev_i32_e32 v241, 31, v240
	v_lshlrev_b64 v[240:241], 11, v[240:241]
	v_cvt_pk_bf16_f32 v239, v22, s0
	v_lshl_add_u64 v[240:241], v[60:61], 0, v[240:241]
	global_store_short v[240:241], v239, off
	v_fma_f32 v22, v22, v196, v212
	v_add_u32_e32 v24, s39, v110
	v_ashrrev_i32_e32 v25, 31, v24
	v_lshlrev_b64 v[24:25], 11, v[24:25]
	v_cvt_pk_bf16_f32 v23, v22, s0
	v_lshl_add_u64 v[24:25], v[60:61], 0, v[24:25]
	global_store_short v[24:25], v23, off
	v_fma_f32 v22, v22, v197, v213
	v_add_u32_e32 v240, s39, v112
	v_ashrrev_i32_e32 v241, 31, v240
	v_lshlrev_b64 v[240:241], 11, v[240:241]
	v_cvt_pk_bf16_f32 v239, v22, s0
	v_lshl_add_u64 v[240:241], v[60:61], 0, v[240:241]
	global_store_short v[240:241], v239, off
	v_fma_f32 v22, v22, v198, v214
	v_add_u32_e32 v24, s39, v114
	v_ashrrev_i32_e32 v25, 31, v24
	v_lshlrev_b64 v[24:25], 11, v[24:25]
	v_cvt_pk_bf16_f32 v23, v22, s0
	v_lshl_add_u64 v[24:25], v[60:61], 0, v[24:25]
	global_store_short v[24:25], v23, off
	v_fma_f32 v22, v22, v199, v215
	v_add_u32_e32 v240, s39, v116
	v_ashrrev_i32_e32 v241, 31, v240
	v_lshlrev_b64 v[240:241], 11, v[240:241]
	v_cvt_pk_bf16_f32 v239, v22, s0
	v_lshl_add_u64 v[240:241], v[60:61], 0, v[240:241]
	global_store_short v[240:241], v239, off
	v_fma_f32 v22, v22, v200, v216
	v_add_u32_e32 v24, s39, v118
	v_ashrrev_i32_e32 v25, 31, v24
	v_lshlrev_b64 v[24:25], 11, v[24:25]
	v_cvt_pk_bf16_f32 v23, v22, s0
	v_lshl_add_u64 v[24:25], v[60:61], 0, v[24:25]
	global_store_short v[24:25], v23, off
	v_fma_f32 v22, v22, v201, v217
	v_add_u32_e32 v240, s39, v120
	v_ashrrev_i32_e32 v241, 31, v240
	v_lshlrev_b64 v[240:241], 11, v[240:241]
	v_cvt_pk_bf16_f32 v239, v22, s0
	v_lshl_add_u64 v[240:241], v[60:61], 0, v[240:241]
	global_store_short v[240:241], v239, off
	v_fma_f32 v22, v22, v202, v218
	v_add_u32_e32 v24, s39, v122
	v_ashrrev_i32_e32 v25, 31, v24
	v_lshlrev_b64 v[24:25], 11, v[24:25]
	v_cvt_pk_bf16_f32 v23, v22, s0
	v_lshl_add_u64 v[24:25], v[60:61], 0, v[24:25]
	global_store_short v[24:25], v23, off
	v_fma_f32 v22, v22, v203, v219
	v_add_u32_e32 v240, s39, v124
	v_ashrrev_i32_e32 v241, 31, v240
	v_lshlrev_b64 v[240:241], 11, v[240:241]
	v_cvt_pk_bf16_f32 v239, v22, s0
	v_lshl_add_u64 v[240:241], v[60:61], 0, v[240:241]
	global_store_short v[240:241], v239, off
	v_fma_f32 v22, v22, v204, v220
	v_add_u32_e32 v24, s39, v126
	v_ashrrev_i32_e32 v25, 31, v24
	v_lshlrev_b64 v[24:25], 11, v[24:25]
	v_cvt_pk_bf16_f32 v23, v22, s0
	v_lshl_add_u64 v[24:25], v[60:61], 0, v[24:25]
	global_store_short v[24:25], v23, off
	v_fma_f32 v22, v22, v205, v221
	v_add_u32_e32 v240, s39, v128
	v_ashrrev_i32_e32 v241, 31, v240
	v_lshlrev_b64 v[240:241], 11, v[240:241]
	v_cvt_pk_bf16_f32 v239, v22, s0
	v_lshl_add_u64 v[240:241], v[60:61], 0, v[240:241]
	global_store_short v[240:241], v239, off
	s_and_saveexec_b64 s[4:5], s[12:13]
	s_cbranch_execz .LBB0_62
	s_lshl_b32 s2, s45, 8
	s_and_b32 s2, s2, 0x100
	v_add_u32_e32 v23, s2, v92
	ds_write_b32 v23, v22
	s_branch .LBB0_62

; __global__ void __launch_bounds__(NTHREADS) mega(Args args) {
	.amdhsa_kernel _Z4mega4Args
		.amdhsa_group_segment_fixed_size 0
		.amdhsa_private_segment_fixed_size 0
		.amdhsa_kernarg_size 464
		.amdhsa_user_sgpr_count 2
		.amdhsa_user_sgpr_dispatch_ptr 0
		.amdhsa_user_sgpr_queue_ptr 0
		.amdhsa_user_sgpr_kernarg_segment_ptr 1
		.amdhsa_user_sgpr_dispatch_id 0
		.amdhsa_user_sgpr_kernarg_preload_length 0
		.amdhsa_user_sgpr_kernarg_preload_offset 0
		.amdhsa_user_sgpr_private_segment_size 0
		.amdhsa_uses_dynamic_stack 0
		.amdhsa_enable_private_segment 0
		.amdhsa_system_sgpr_workgroup_id_x 1
		.amdhsa_system_sgpr_workgroup_id_y 0
		.amdhsa_system_sgpr_workgroup_id_z 0
		.amdhsa_system_sgpr_workgroup_info 0
		.amdhsa_system_vgpr_workitem_id 2
		.amdhsa_next_free_vgpr 256
		.amdhsa_next_free_sgpr 102
		.amdhsa_accum_offset 256
		.amdhsa_reserve_vcc 1
		.amdhsa_float_round_mode_32 0
		.amdhsa_float_round_mode_16_64 0
		.amdhsa_float_denorm_mode_32 3
		.amdhsa_float_denorm_mode_16_64 3
		.amdhsa_dx10_clamp 1
		.amdhsa_ieee_mode 1
		.amdhsa_fp16_overflow 0
		.amdhsa_tg_split 0
		.amdhsa_exception_fp_ieee_invalid_op 0
		.amdhsa_exception_fp_denorm_src 0
		.amdhsa_exception_fp_ieee_div_zero 0
		.amdhsa_exception_fp_ieee_overflow 0
		.amdhsa_exception_fp_ieee_underflow 0
		.amdhsa_exception_fp_ieee_inexact 0
		.amdhsa_exception_int_div_zero 0
	.end_amdhsa_kernel

; __global__ void __launch_bounds__(NTHREADS) mega(Args args) {
amdhsa.kernels:
  - .agpr_count:     0
    .args:
      - .offset:         0
        .size:           208
        .value_kind:     by_value
      - .offset:         208
        .size:           4
        .value_kind:     hidden_block_count_x
      - .offset:         212
        .size:           4
        .value_kind:     hidden_block_count_y
      - .offset:         216
        .size:           4
        .value_kind:     hidden_block_count_z
      - .offset:         220
        .size:           2
        .value_kind:     hidden_group_size_x
      - .offset:         222
        .size:           2
        .value_kind:     hidden_group_size_y
      - .offset:         224
        .size:           2
        .value_kind:     hidden_group_size_z
      - .offset:         226
        .size:           2
        .value_kind:     hidden_remainder_x
      - .offset:         228
        .size:           2
        .value_kind:     hidden_remainder_y
      - .offset:         230
        .size:           2
        .value_kind:     hidden_remainder_z
      - .offset:         248
        .size:           8
        .value_kind:     hidden_global_offset_x
      - .offset:         256
        .size:           8
        .value_kind:     hidden_global_offset_y
      - .offset:         264
        .size:           8
        .value_kind:     hidden_global_offset_z
      - .offset:         272
        .size:           2
        .value_kind:     hidden_grid_dims
      - .offset:         296
        .size:           8
        .value_kind:     hidden_multigrid_sync_arg
      - .offset:         328
        .size:           4
        .value_kind:     hidden_dynamic_lds_size
    .group_segment_fixed_size: 0
    .kernarg_segment_align: 8
    .kernarg_segment_size: 464
    .language:       OpenCL C
    .language_version:
      - 2
      - 0
    .max_flat_workgroup_size: 512
    .name:           _Z4mega4Args
    .private_segment_fixed_size: 0
    .sgpr_count:     108
    .sgpr_spill_count: 127
    .symbol:         _Z4mega4Args.kd
    .uniform_work_group_size: 1
    .uses_dynamic_stack: false
    .vgpr_count:     256
    .vgpr_spill_count: 0
    .wavefront_size: 64
